# GEMM MMA blocks reordered: both k-steps of an accumulator tile issued back to back, serpentine over tiles (same per-accumulator summation order)
# speedup vs baseline: 1.0242x; 1.0147x over previous
.LBB0_200:
	ds_read_b128 v[150:153], v161
	ds_read_b128 v[154:157], v161 offset:1024
	ds_read_b128 v[166:169], v161 offset:2048
	ds_read_b128 v[170:173], v161 offset:3072
	ds_read_b128 v[174:177], v162
	ds_read_b128 v[178:181], v162 offset:1024
	ds_read_b128 v[182:185], v162 offset:2048
	ds_read_b128 v[186:189], v162 offset:3072
	s_add_u32 s8, s55, s26
	s_addc_u32 s9, s63, 0
	s_cmp_eq_u32 s26, s4
	s_cselect_b32 s23, s0, s9
	s_cselect_b32 s22, s1, s8
	s_cselect_b32 s9, s41, s54
	s_cselect_b32 s8, s43, s53
	s_add_i32 s65, s18, 0xc000
	v_lshl_add_u64 v[144:145], v[2:3], 0, s[26:27]
	s_mov_b32 m0, s65
	s_add_i32 s64, s18, 0xe000
	ds_read_b128 v[190:193], v163
	ds_read_b128 v[194:197], v163 offset:1024
	ds_read_b128 v[198:201], v163 offset:2048
	ds_read_b128 v[202:205], v163 offset:3072
	ds_read_b128 v[206:209], v163 offset:4096
	ds_read_b128 v[210:213], v163 offset:5120
	ds_read_b128 v[214:217], v163 offset:6144
	ds_read_b128 v[218:221], v163 offset:7168
	global_load_lds_dwordx4 v[144:145], off
	v_lshl_add_u64 v[144:145], v[148:149], 0, s[26:27]
	s_mov_b32 m0, s64
	s_nop 0
	global_load_lds_dwordx4 v[144:145], off
	s_waitcnt vmcnt(8)
	s_waitcnt lgkmcnt(0)
	s_barrier
	v_mfma_f32_16x16x32_bf16 v[128:131], v[150:153], v[190:193], v[128:131]
	v_mfma_f32_16x16x32_bf16 v[128:131], v[154:157], v[194:197], v[128:131]
	v_mfma_f32_16x16x32_bf16 v[124:127], v[166:169], v[190:193], v[124:127]
	v_mfma_f32_16x16x32_bf16 v[124:127], v[170:173], v[194:197], v[124:127]
	v_mfma_f32_16x16x32_bf16 v[108:111], v[166:169], v[198:201], v[108:111]
	v_mfma_f32_16x16x32_bf16 v[108:111], v[170:173], v[202:205], v[108:111]
	v_mfma_f32_16x16x32_bf16 v[112:115], v[150:153], v[198:201], v[112:115]
	v_mfma_f32_16x16x32_bf16 v[112:115], v[154:157], v[202:205], v[112:115]
	v_mfma_f32_16x16x32_bf16 v[96:99], v[150:153], v[206:209], v[96:99]
	v_mfma_f32_16x16x32_bf16 v[96:99], v[154:157], v[210:213], v[96:99]
	v_mfma_f32_16x16x32_bf16 v[92:95], v[166:169], v[206:209], v[92:95]
	v_mfma_f32_16x16x32_bf16 v[92:95], v[170:173], v[210:213], v[92:95]
	v_mfma_f32_16x16x32_bf16 v[76:79], v[166:169], v[214:217], v[76:79]
	v_mfma_f32_16x16x32_bf16 v[76:79], v[170:173], v[218:221], v[76:79]
	v_mfma_f32_16x16x32_bf16 v[80:83], v[150:153], v[214:217], v[80:83]
	v_mfma_f32_16x16x32_bf16 v[80:83], v[154:157], v[218:221], v[80:83]
	v_mfma_f32_16x16x32_bf16 v[72:75], v[174:177], v[214:217], v[72:75]
	v_mfma_f32_16x16x32_bf16 v[72:75], v[178:181], v[218:221], v[72:75]
	v_mfma_f32_16x16x32_bf16 v[68:71], v[182:185], v[214:217], v[68:71]
	v_mfma_f32_16x16x32_bf16 v[68:71], v[186:189], v[218:221], v[68:71]
	v_mfma_f32_16x16x32_bf16 v[84:87], v[182:185], v[206:209], v[84:87]
	v_mfma_f32_16x16x32_bf16 v[84:87], v[186:189], v[210:213], v[84:87]
	v_mfma_f32_16x16x32_bf16 v[88:91], v[174:177], v[206:209], v[88:91]
	v_mfma_f32_16x16x32_bf16 v[88:91], v[178:181], v[210:213], v[88:91]
	v_mfma_f32_16x16x32_bf16 v[104:107], v[174:177], v[198:201], v[104:107]
	v_mfma_f32_16x16x32_bf16 v[104:107], v[178:181], v[202:205], v[104:107]
	v_mfma_f32_16x16x32_bf16 v[100:103], v[182:185], v[198:201], v[100:103]
	v_mfma_f32_16x16x32_bf16 v[100:103], v[186:189], v[202:205], v[100:103]
	v_mfma_f32_16x16x32_bf16 v[116:119], v[182:185], v[190:193], v[116:119]
	v_mfma_f32_16x16x32_bf16 v[116:119], v[186:189], v[194:197], v[116:119]
	v_mfma_f32_16x16x32_bf16 v[120:123], v[174:177], v[190:193], v[120:123]
	v_mfma_f32_16x16x32_bf16 v[120:123], v[178:181], v[194:197], v[120:123]
	s_barrier
	s_add_i32 s12, s60, s17
	v_lshl_add_u64 v[144:145], s[8:9], 0, v[134:135]
	s_mov_b32 m0, s12
	ds_read_b128 v[190:193], v163 offset:16384
	ds_read_b128 v[194:197], v163 offset:17408
	ds_read_b128 v[198:201], v163 offset:18432
	ds_read_b128 v[202:205], v163 offset:19456
	ds_read_b128 v[206:209], v163 offset:20480
	ds_read_b128 v[210:213], v163 offset:21504
	ds_read_b128 v[214:217], v163 offset:22528
	ds_read_b128 v[218:221], v163 offset:23552
	global_load_lds_dwordx4 v[144:145], off
	s_add_i32 m0, s12, 0x2000
	s_add_u32 s12, s8, 0x4000
	v_lshl_add_u64 v[144:145], s[8:9], 0, v[138:139]
	s_addc_u32 s13, s9, 0
	s_add_i32 s14, s61, s17
	global_load_lds_dwordx4 v[144:145], off
	v_lshl_add_u64 v[144:145], s[12:13], 0, v[134:135]
	s_mov_b32 m0, s14
	v_lshl_add_u64 v[222:223], s[22:23], 0, v[136:137]
	global_load_lds_dwordx4 v[144:145], off
	v_lshl_add_u64 v[144:145], s[12:13], 0, v[138:139]
	s_add_i32 m0, s14, 0x2000
	s_nop 0
	global_load_lds_dwordx4 v[144:145], off
	v_lshl_add_u64 v[144:145], s[22:23], 0, v[132:133]
	s_mov_b32 m0, s18
	s_nop 0
	global_load_lds_dwordx4 v[144:145], off
	s_mov_b32 m0, s19
	s_nop 0
	global_load_lds_dwordx4 v[222:223], off
	s_waitcnt vmcnt(8)
	s_waitcnt lgkmcnt(0)
	s_barrier
	v_mfma_f32_16x16x32_bf16 v[64:67], v[150:153], v[190:193], v[64:67]
	v_mfma_f32_16x16x32_bf16 v[64:67], v[154:157], v[194:197], v[64:67]
	v_mfma_f32_16x16x32_bf16 v[60:63], v[166:169], v[190:193], v[60:63]
	v_mfma_f32_16x16x32_bf16 v[60:63], v[170:173], v[194:197], v[60:63]
	v_mfma_f32_16x16x32_bf16 v[44:47], v[166:169], v[198:201], v[44:47]
	v_mfma_f32_16x16x32_bf16 v[44:47], v[170:173], v[202:205], v[44:47]
	v_mfma_f32_16x16x32_bf16 v[48:51], v[150:153], v[198:201], v[48:51]
	v_mfma_f32_16x16x32_bf16 v[48:51], v[154:157], v[202:205], v[48:51]
	v_mfma_f32_16x16x32_bf16 v[32:35], v[150:153], v[206:209], v[32:35]
	v_mfma_f32_16x16x32_bf16 v[32:35], v[154:157], v[210:213], v[32:35]
	v_mfma_f32_16x16x32_bf16 v[28:31], v[166:169], v[206:209], v[28:31]
	v_mfma_f32_16x16x32_bf16 v[28:31], v[170:173], v[210:213], v[28:31]
	v_mfma_f32_16x16x32_bf16 v[12:15], v[166:169], v[214:217], v[12:15]
	v_mfma_f32_16x16x32_bf16 v[12:15], v[170:173], v[218:221], v[12:15]
	v_mfma_f32_16x16x32_bf16 v[16:19], v[150:153], v[214:217], v[16:19]
	v_mfma_f32_16x16x32_bf16 v[16:19], v[154:157], v[218:221], v[16:19]
	v_mfma_f32_16x16x32_bf16 v[8:11], v[174:177], v[214:217], v[8:11]
	v_mfma_f32_16x16x32_bf16 v[8:11], v[178:181], v[218:221], v[8:11]
	v_mfma_f32_16x16x32_bf16 v[4:7], v[182:185], v[214:217], v[4:7]
	v_mfma_f32_16x16x32_bf16 v[4:7], v[186:189], v[218:221], v[4:7]
	v_mfma_f32_16x16x32_bf16 v[20:23], v[182:185], v[206:209], v[20:23]
	v_mfma_f32_16x16x32_bf16 v[20:23], v[186:189], v[210:213], v[20:23]
	v_mfma_f32_16x16x32_bf16 v[24:27], v[174:177], v[206:209], v[24:27]
	v_mfma_f32_16x16x32_bf16 v[24:27], v[178:181], v[210:213], v[24:27]
	v_mfma_f32_16x16x32_bf16 v[40:43], v[174:177], v[198:201], v[40:43]
	v_mfma_f32_16x16x32_bf16 v[40:43], v[178:181], v[202:205], v[40:43]
	v_mfma_f32_16x16x32_bf16 v[36:39], v[182:185], v[198:201], v[36:39]
	v_mfma_f32_16x16x32_bf16 v[36:39], v[186:189], v[202:205], v[36:39]
	v_mfma_f32_16x16x32_bf16 v[52:55], v[182:185], v[190:193], v[52:55]
	v_mfma_f32_16x16x32_bf16 v[52:55], v[186:189], v[194:197], v[52:55]
	v_mfma_f32_16x16x32_bf16 v[56:59], v[174:177], v[190:193], v[56:59]
	v_mfma_f32_16x16x32_bf16 v[56:59], v[178:181], v[194:197], v[56:59]
	s_barrier
	s_add_i32 s14, 0, 0x18000
	v_add_u32_e32 v1, s14, v160
	s_add_i32 s66, 0, 0x1c000
	ds_read_b128 v[150:153], v1
	ds_read_b128 v[154:157], v1 offset:1024
	ds_read_b128 v[166:169], v1 offset:2048
	ds_read_b128 v[170:173], v1 offset:3072
	v_add_u32_e32 v1, s66, v160
	ds_read_b128 v[174:177], v1
	ds_read_b128 v[178:181], v1 offset:1024
	ds_read_b128 v[182:185], v1 offset:2048
	ds_read_b128 v[186:189], v1 offset:3072
	s_add_u32 s12, s22, 0x100000
	s_addc_u32 s13, s23, 0
	s_mov_b32 m0, s20
	v_lshl_add_u64 v[224:225], s[12:13], 0, v[132:133]
	ds_read_b128 v[190:193], v163 offset:32768
	ds_read_b128 v[194:197], v163 offset:33792
	ds_read_b128 v[198:201], v163 offset:34816
	ds_read_b128 v[202:205], v163 offset:35840
	ds_read_b128 v[206:209], v163 offset:36864
	ds_read_b128 v[210:213], v163 offset:37888
	ds_read_b128 v[214:217], v163 offset:38912
	ds_read_b128 v[218:221], v163 offset:39936
	global_load_lds_dwordx4 v[224:225], off
	v_lshl_add_u64 v[224:225], s[12:13], 0, v[136:137]
	s_mov_b32 m0, s21
	s_nop 0
	global_load_lds_dwordx4 v[224:225], off
	s_waitcnt vmcnt(8)
	s_waitcnt lgkmcnt(0)
	s_barrier
	v_mfma_f32_16x16x32_bf16 v[128:131], v[150:153], v[190:193], v[128:131]
	v_mfma_f32_16x16x32_bf16 v[128:131], v[154:157], v[194:197], v[128:131]
	v_mfma_f32_16x16x32_bf16 v[124:127], v[166:169], v[190:193], v[124:127]
	v_mfma_f32_16x16x32_bf16 v[124:127], v[170:173], v[194:197], v[124:127]
	v_mfma_f32_16x16x32_bf16 v[108:111], v[166:169], v[198:201], v[108:111]
	v_mfma_f32_16x16x32_bf16 v[108:111], v[170:173], v[202:205], v[108:111]
	v_mfma_f32_16x16x32_bf16 v[112:115], v[150:153], v[198:201], v[112:115]
	v_mfma_f32_16x16x32_bf16 v[112:115], v[154:157], v[202:205], v[112:115]
	v_mfma_f32_16x16x32_bf16 v[96:99], v[150:153], v[206:209], v[96:99]
	v_mfma_f32_16x16x32_bf16 v[96:99], v[154:157], v[210:213], v[96:99]
	v_mfma_f32_16x16x32_bf16 v[92:95], v[166:169], v[206:209], v[92:95]
	v_mfma_f32_16x16x32_bf16 v[92:95], v[170:173], v[210:213], v[92:95]
	v_mfma_f32_16x16x32_bf16 v[76:79], v[166:169], v[214:217], v[76:79]
	v_mfma_f32_16x16x32_bf16 v[76:79], v[170:173], v[218:221], v[76:79]
	v_mfma_f32_16x16x32_bf16 v[80:83], v[150:153], v[214:217], v[80:83]
	v_mfma_f32_16x16x32_bf16 v[80:83], v[154:157], v[218:221], v[80:83]
	v_mfma_f32_16x16x32_bf16 v[72:75], v[174:177], v[214:217], v[72:75]
	v_mfma_f32_16x16x32_bf16 v[72:75], v[178:181], v[218:221], v[72:75]
	v_mfma_f32_16x16x32_bf16 v[68:71], v[182:185], v[214:217], v[68:71]
	v_mfma_f32_16x16x32_bf16 v[68:71], v[186:189], v[218:221], v[68:71]
	v_mfma_f32_16x16x32_bf16 v[84:87], v[182:185], v[206:209], v[84:87]
	v_mfma_f32_16x16x32_bf16 v[84:87], v[186:189], v[210:213], v[84:87]
	v_mfma_f32_16x16x32_bf16 v[88:91], v[174:177], v[206:209], v[88:91]
	v_mfma_f32_16x16x32_bf16 v[88:91], v[178:181], v[210:213], v[88:91]
	v_mfma_f32_16x16x32_bf16 v[104:107], v[174:177], v[198:201], v[104:107]
	v_mfma_f32_16x16x32_bf16 v[104:107], v[178:181], v[202:205], v[104:107]
	v_mfma_f32_16x16x32_bf16 v[100:103], v[182:185], v[198:201], v[100:103]
	v_mfma_f32_16x16x32_bf16 v[100:103], v[186:189], v[202:205], v[100:103]
	v_mfma_f32_16x16x32_bf16 v[116:119], v[182:185], v[190:193], v[116:119]
	v_mfma_f32_16x16x32_bf16 v[116:119], v[186:189], v[194:197], v[116:119]
	v_mfma_f32_16x16x32_bf16 v[120:123], v[174:177], v[190:193], v[120:123]
	v_mfma_f32_16x16x32_bf16 v[120:123], v[178:181], v[194:197], v[120:123]
	s_barrier
	s_add_u32 s12, s8, 0x8000
	s_addc_u32 s13, s9, 0
	s_add_i32 s14, s14, s17
	v_lshl_add_u64 v[224:225], s[12:13], 0, v[134:135]
	s_mov_b32 m0, s14
	ds_read_b128 v[190:193], v163 offset:49152
	ds_read_b128 v[194:197], v163 offset:50176
	ds_read_b128 v[198:201], v163 offset:51200
	ds_read_b128 v[202:205], v163 offset:52224
	ds_read_b128 v[206:209], v163 offset:53248
	ds_read_b128 v[210:213], v163 offset:54272
	ds_read_b128 v[214:217], v163 offset:55296
	ds_read_b128 v[218:221], v163 offset:56320
	global_load_lds_dwordx4 v[224:225], off
	s_add_i32 m0, s14, 0x2000
	s_add_u32 s8, s8, 0xc000
	v_lshl_add_u64 v[224:225], s[12:13], 0, v[138:139]
	s_addc_u32 s9, s9, 0
	s_add_i32 s12, s66, s17
	global_load_lds_dwordx4 v[224:225], off
	v_lshl_add_u64 v[224:225], s[8:9], 0, v[134:135]
	s_mov_b32 m0, s12
	v_lshl_add_u64 v[144:145], v[144:145], 0, s[30:31]
	global_load_lds_dwordx4 v[224:225], off
	v_lshl_add_u64 v[224:225], s[8:9], 0, v[138:139]
	s_add_i32 m0, s12, 0x2000
	s_nop 0
	global_load_lds_dwordx4 v[224:225], off
	s_mov_b32 m0, s51
	s_nop 0
	global_load_lds_dwordx4 v[144:145], off
	v_lshl_add_u64 v[144:145], v[222:223], 0, s[30:31]
	s_mov_b32 m0, s56
	s_nop 0
	global_load_lds_dwordx4 v[144:145], off
	s_waitcnt vmcnt(8)
	s_waitcnt lgkmcnt(0)
	s_barrier
	v_mfma_f32_16x16x32_bf16 v[64:67], v[150:153], v[190:193], v[64:67]
	v_mfma_f32_16x16x32_bf16 v[64:67], v[154:157], v[194:197], v[64:67]
	v_mfma_f32_16x16x32_bf16 v[60:63], v[166:169], v[190:193], v[60:63]
	v_mfma_f32_16x16x32_bf16 v[60:63], v[170:173], v[194:197], v[60:63]
	v_mfma_f32_16x16x32_bf16 v[44:47], v[166:169], v[198:201], v[44:47]
	v_mfma_f32_16x16x32_bf16 v[44:47], v[170:173], v[202:205], v[44:47]
	v_mfma_f32_16x16x32_bf16 v[48:51], v[150:153], v[198:201], v[48:51]
	v_mfma_f32_16x16x32_bf16 v[48:51], v[154:157], v[202:205], v[48:51]
	v_mfma_f32_16x16x32_bf16 v[32:35], v[150:153], v[206:209], v[32:35]
	v_mfma_f32_16x16x32_bf16 v[32:35], v[154:157], v[210:213], v[32:35]
	v_mfma_f32_16x16x32_bf16 v[28:31], v[166:169], v[206:209], v[28:31]
	v_mfma_f32_16x16x32_bf16 v[28:31], v[170:173], v[210:213], v[28:31]
	v_mfma_f32_16x16x32_bf16 v[12:15], v[166:169], v[214:217], v[12:15]
	v_mfma_f32_16x16x32_bf16 v[12:15], v[170:173], v[218:221], v[12:15]
	v_mfma_f32_16x16x32_bf16 v[16:19], v[150:153], v[214:217], v[16:19]
	v_mfma_f32_16x16x32_bf16 v[16:19], v[154:157], v[218:221], v[16:19]
	v_mfma_f32_16x16x32_bf16 v[8:11], v[174:177], v[214:217], v[8:11]
	v_mfma_f32_16x16x32_bf16 v[8:11], v[178:181], v[218:221], v[8:11]
	v_mfma_f32_16x16x32_bf16 v[4:7], v[182:185], v[214:217], v[4:7]
	v_mfma_f32_16x16x32_bf16 v[4:7], v[186:189], v[218:221], v[4:7]
	v_mfma_f32_16x16x32_bf16 v[20:23], v[182:185], v[206:209], v[20:23]
	v_mfma_f32_16x16x32_bf16 v[20:23], v[186:189], v[210:213], v[20:23]
	v_mfma_f32_16x16x32_bf16 v[24:27], v[174:177], v[206:209], v[24:27]
	v_mfma_f32_16x16x32_bf16 v[24:27], v[178:181], v[210:213], v[24:27]
	v_mfma_f32_16x16x32_bf16 v[40:43], v[174:177], v[198:201], v[40:43]
	v_mfma_f32_16x16x32_bf16 v[40:43], v[178:181], v[202:205], v[40:43]
	v_mfma_f32_16x16x32_bf16 v[36:39], v[182:185], v[198:201], v[36:39]
	v_mfma_f32_16x16x32_bf16 v[36:39], v[186:189], v[202:205], v[36:39]
	v_mfma_f32_16x16x32_bf16 v[52:55], v[182:185], v[190:193], v[52:55]
	v_mfma_f32_16x16x32_bf16 v[52:55], v[186:189], v[194:197], v[52:55]
	v_mfma_f32_16x16x32_bf16 v[56:59], v[174:177], v[190:193], v[56:59]
	v_mfma_f32_16x16x32_bf16 v[56:59], v[178:181], v[194:197], v[56:59]
	s_barrier
	s_add_i32 s52, s52, 2
	s_add_u32 s53, s53, 0x10000
	s_addc_u32 s54, s54, 0
	s_add_u32 s55, s55, 0x100
	s_addc_u32 s63, s63, 0
	s_add_u32 s4, s4, 0xffffff00
	s_addc_u32 s5, s5, -1
	v_lshl_add_u64 v[2:3], v[2:3], 0, s[36:37]
	s_cmp_gt_u32 s52, 61
	v_lshl_add_u64 v[148:149], v[148:149], 0, s[36:37]
	s_cbranch_scc0 .LBB0_200
	s_and_b64 vcc, exec, s[34:35]
	s_cbranch_vccz .LBB0_203
	s_barrier

.LBB0_510:
	ds_read_b128 v[158:161], v153
	ds_read_b128 v[162:165], v153 offset:1024
	ds_read_b128 v[166:169], v153 offset:2048
	ds_read_b128 v[170:173], v153 offset:3072
	ds_read_b128 v[174:177], v154
	ds_read_b128 v[178:181], v154 offset:1024
	ds_read_b128 v[182:185], v154 offset:2048
	ds_read_b128 v[186:189], v154 offset:3072
	s_add_u32 s12, s64, s26
	s_addc_u32 s13, s65, 0
	s_cmp_eq_u32 s26, s8
	s_cselect_b32 s23, s0, s13
	s_cselect_b32 s22, s1, s12
	s_cselect_b32 s57, s45, s63
	s_cselect_b32 s56, s47, s62
	s_add_i32 s67, s18, 0xc000
	v_lshl_add_u64 v[144:145], v[2:3], 0, s[26:27]
	s_mov_b32 m0, s67
	s_add_i32 s66, s18, 0xe000
	ds_read_b128 v[190:193], v155
	ds_read_b128 v[194:197], v155 offset:1024
	ds_read_b128 v[198:201], v155 offset:2048
	ds_read_b128 v[202:205], v155 offset:3072
	ds_read_b128 v[206:209], v155 offset:4096
	ds_read_b128 v[210:213], v155 offset:5120
	ds_read_b128 v[214:217], v155 offset:6144
	ds_read_b128 v[218:221], v155 offset:7168
	global_load_lds_dwordx4 v[144:145], off
	v_lshl_add_u64 v[144:145], v[148:149], 0, s[26:27]
	s_mov_b32 m0, s66
	s_nop 0
	global_load_lds_dwordx4 v[144:145], off
	s_waitcnt vmcnt(8)
	s_waitcnt lgkmcnt(0)
	s_barrier
	v_mfma_f32_16x16x32_bf16 v[128:131], v[158:161], v[190:193], v[128:131]
	v_mfma_f32_16x16x32_bf16 v[128:131], v[162:165], v[194:197], v[128:131]
	v_mfma_f32_16x16x32_bf16 v[116:119], v[166:169], v[190:193], v[116:119]
	v_mfma_f32_16x16x32_bf16 v[116:119], v[170:173], v[194:197], v[116:119]
	v_mfma_f32_16x16x32_bf16 v[100:103], v[166:169], v[198:201], v[100:103]
	v_mfma_f32_16x16x32_bf16 v[100:103], v[170:173], v[202:205], v[100:103]
	v_mfma_f32_16x16x32_bf16 v[112:115], v[158:161], v[198:201], v[112:115]
	v_mfma_f32_16x16x32_bf16 v[112:115], v[162:165], v[202:205], v[112:115]
	v_mfma_f32_16x16x32_bf16 v[96:99], v[158:161], v[206:209], v[96:99]
	v_mfma_f32_16x16x32_bf16 v[96:99], v[162:165], v[210:213], v[96:99]
	v_mfma_f32_16x16x32_bf16 v[84:87], v[166:169], v[206:209], v[84:87]
	v_mfma_f32_16x16x32_bf16 v[84:87], v[170:173], v[210:213], v[84:87]
	v_mfma_f32_16x16x32_bf16 v[64:67], v[166:169], v[214:217], v[64:67]
	v_mfma_f32_16x16x32_bf16 v[64:67], v[170:173], v[218:221], v[64:67]
	v_mfma_f32_16x16x32_bf16 v[80:83], v[158:161], v[214:217], v[80:83]
	v_mfma_f32_16x16x32_bf16 v[80:83], v[162:165], v[218:221], v[80:83]
	v_mfma_f32_16x16x32_bf16 v[72:75], v[174:177], v[214:217], v[72:75]
	v_mfma_f32_16x16x32_bf16 v[72:75], v[178:181], v[218:221], v[72:75]
	v_mfma_f32_16x16x32_bf16 v[68:71], v[182:185], v[214:217], v[68:71]
	v_mfma_f32_16x16x32_bf16 v[68:71], v[186:189], v[218:221], v[68:71]
	v_mfma_f32_16x16x32_bf16 v[88:91], v[182:185], v[206:209], v[88:91]
	v_mfma_f32_16x16x32_bf16 v[88:91], v[186:189], v[210:213], v[88:91]
	v_mfma_f32_16x16x32_bf16 v[92:95], v[174:177], v[206:209], v[92:95]
	v_mfma_f32_16x16x32_bf16 v[92:95], v[178:181], v[210:213], v[92:95]
	v_mfma_f32_16x16x32_bf16 v[108:111], v[174:177], v[198:201], v[108:111]
	v_mfma_f32_16x16x32_bf16 v[108:111], v[178:181], v[202:205], v[108:111]
	v_mfma_f32_16x16x32_bf16 v[104:107], v[182:185], v[198:201], v[104:107]
	v_mfma_f32_16x16x32_bf16 v[104:107], v[186:189], v[202:205], v[104:107]
	v_mfma_f32_16x16x32_bf16 v[120:123], v[182:185], v[190:193], v[120:123]
	v_mfma_f32_16x16x32_bf16 v[120:123], v[186:189], v[194:197], v[120:123]
	v_mfma_f32_16x16x32_bf16 v[124:127], v[174:177], v[190:193], v[124:127]
	v_mfma_f32_16x16x32_bf16 v[124:127], v[178:181], v[194:197], v[124:127]
	s_barrier
	s_add_i32 s12, s58, s17
	v_lshl_add_u64 v[144:145], s[56:57], 0, v[134:135]
	s_mov_b32 m0, s12
	ds_read_b128 v[190:193], v155 offset:16384
	ds_read_b128 v[194:197], v155 offset:17408
	ds_read_b128 v[198:201], v155 offset:18432
	ds_read_b128 v[202:205], v155 offset:19456
	ds_read_b128 v[206:209], v155 offset:20480
	ds_read_b128 v[210:213], v155 offset:21504
	ds_read_b128 v[214:217], v155 offset:22528
	ds_read_b128 v[218:221], v155 offset:23552
	global_load_lds_dwordx4 v[144:145], off
	s_add_i32 m0, s12, 0x2000
	s_add_u32 s12, s56, 0x4000
	v_lshl_add_u64 v[144:145], s[56:57], 0, v[138:139]
	s_addc_u32 s13, s57, 0
	s_add_i32 s14, s59, s17
	global_load_lds_dwordx4 v[144:145], off
	v_lshl_add_u64 v[144:145], s[12:13], 0, v[134:135]
	s_mov_b32 m0, s14
	v_lshl_add_u64 v[222:223], s[22:23], 0, v[136:137]
	global_load_lds_dwordx4 v[144:145], off
	v_lshl_add_u64 v[144:145], s[12:13], 0, v[138:139]
	s_add_i32 m0, s14, 0x2000
	s_nop 0
	global_load_lds_dwordx4 v[144:145], off
	v_lshl_add_u64 v[144:145], s[22:23], 0, v[132:133]
	s_mov_b32 m0, s18
	s_nop 0
	global_load_lds_dwordx4 v[144:145], off
	s_mov_b32 m0, s19
	s_nop 0
	global_load_lds_dwordx4 v[222:223], off
	s_waitcnt vmcnt(8)
	s_waitcnt lgkmcnt(0)
	s_barrier
	v_mfma_f32_16x16x32_bf16 v[76:79], v[158:161], v[190:193], v[76:79]
	v_mfma_f32_16x16x32_bf16 v[76:79], v[162:165], v[194:197], v[76:79]
	v_mfma_f32_16x16x32_bf16 v[52:55], v[166:169], v[190:193], v[52:55]
	v_mfma_f32_16x16x32_bf16 v[52:55], v[170:173], v[194:197], v[52:55]
	v_mfma_f32_16x16x32_bf16 v[36:39], v[166:169], v[198:201], v[36:39]
	v_mfma_f32_16x16x32_bf16 v[36:39], v[170:173], v[202:205], v[36:39]
	v_mfma_f32_16x16x32_bf16 v[48:51], v[158:161], v[198:201], v[48:51]
	v_mfma_f32_16x16x32_bf16 v[48:51], v[162:165], v[202:205], v[48:51]
	v_mfma_f32_16x16x32_bf16 v[32:35], v[158:161], v[206:209], v[32:35]
	v_mfma_f32_16x16x32_bf16 v[32:35], v[162:165], v[210:213], v[32:35]
	v_mfma_f32_16x16x32_bf16 v[20:23], v[166:169], v[206:209], v[20:23]
	v_mfma_f32_16x16x32_bf16 v[20:23], v[170:173], v[210:213], v[20:23]
	v_mfma_f32_16x16x32_bf16 v[4:7], v[166:169], v[214:217], v[4:7]
	v_mfma_f32_16x16x32_bf16 v[4:7], v[170:173], v[218:221], v[4:7]
	v_mfma_f32_16x16x32_bf16 v[16:19], v[158:161], v[214:217], v[16:19]
	v_mfma_f32_16x16x32_bf16 v[16:19], v[162:165], v[218:221], v[16:19]
	v_mfma_f32_16x16x32_bf16 v[12:15], v[174:177], v[214:217], v[12:15]
	v_mfma_f32_16x16x32_bf16 v[12:15], v[178:181], v[218:221], v[12:15]
	v_mfma_f32_16x16x32_bf16 v[8:11], v[182:185], v[214:217], v[8:11]
	v_mfma_f32_16x16x32_bf16 v[8:11], v[186:189], v[218:221], v[8:11]
	v_mfma_f32_16x16x32_bf16 v[24:27], v[182:185], v[206:209], v[24:27]
	v_mfma_f32_16x16x32_bf16 v[24:27], v[186:189], v[210:213], v[24:27]
	v_mfma_f32_16x16x32_bf16 v[28:31], v[174:177], v[206:209], v[28:31]
	v_mfma_f32_16x16x32_bf16 v[28:31], v[178:181], v[210:213], v[28:31]
	v_mfma_f32_16x16x32_bf16 v[44:47], v[174:177], v[198:201], v[44:47]
	v_mfma_f32_16x16x32_bf16 v[44:47], v[178:181], v[202:205], v[44:47]
	v_mfma_f32_16x16x32_bf16 v[40:43], v[182:185], v[198:201], v[40:43]
	v_mfma_f32_16x16x32_bf16 v[40:43], v[186:189], v[202:205], v[40:43]
	v_mfma_f32_16x16x32_bf16 v[56:59], v[182:185], v[190:193], v[56:59]
	v_mfma_f32_16x16x32_bf16 v[56:59], v[186:189], v[194:197], v[56:59]
	v_mfma_f32_16x16x32_bf16 v[60:63], v[174:177], v[190:193], v[60:63]
	v_mfma_f32_16x16x32_bf16 v[60:63], v[178:181], v[194:197], v[60:63]
	s_barrier
	s_add_i32 s14, 0, 0x18000
	v_add_u32_e32 v1, s14, v151
	s_add_i32 s68, 0, 0x1c000
	ds_read_b128 v[158:161], v1
	ds_read_b128 v[162:165], v1 offset:1024
	ds_read_b128 v[166:169], v1 offset:2048
	ds_read_b128 v[170:173], v1 offset:3072
	v_add_u32_e32 v1, s68, v151
	ds_read_b128 v[174:177], v1
	ds_read_b128 v[178:181], v1 offset:1024
	ds_read_b128 v[182:185], v1 offset:2048
	ds_read_b128 v[186:189], v1 offset:3072
	s_add_u32 s12, s22, 0x100000
	s_addc_u32 s13, s23, 0
	s_mov_b32 m0, s20
	v_lshl_add_u64 v[224:225], s[12:13], 0, v[132:133]
	ds_read_b128 v[190:193], v155 offset:32768
	ds_read_b128 v[194:197], v155 offset:33792
	ds_read_b128 v[198:201], v155 offset:34816
	ds_read_b128 v[202:205], v155 offset:35840
	ds_read_b128 v[206:209], v155 offset:36864
	ds_read_b128 v[210:213], v155 offset:37888
	ds_read_b128 v[214:217], v155 offset:38912
	ds_read_b128 v[218:221], v155 offset:39936
	global_load_lds_dwordx4 v[224:225], off
	v_lshl_add_u64 v[224:225], s[12:13], 0, v[136:137]
	s_mov_b32 m0, s21
	s_nop 0
	global_load_lds_dwordx4 v[224:225], off
	s_waitcnt vmcnt(8)
	s_waitcnt lgkmcnt(0)
	s_barrier
	v_mfma_f32_16x16x32_bf16 v[128:131], v[158:161], v[190:193], v[128:131]
	v_mfma_f32_16x16x32_bf16 v[128:131], v[162:165], v[194:197], v[128:131]
	v_mfma_f32_16x16x32_bf16 v[116:119], v[166:169], v[190:193], v[116:119]
	v_mfma_f32_16x16x32_bf16 v[116:119], v[170:173], v[194:197], v[116:119]
	v_mfma_f32_16x16x32_bf16 v[100:103], v[166:169], v[198:201], v[100:103]
	v_mfma_f32_16x16x32_bf16 v[100:103], v[170:173], v[202:205], v[100:103]
	v_mfma_f32_16x16x32_bf16 v[112:115], v[158:161], v[198:201], v[112:115]
	v_mfma_f32_16x16x32_bf16 v[112:115], v[162:165], v[202:205], v[112:115]
	v_mfma_f32_16x16x32_bf16 v[96:99], v[158:161], v[206:209], v[96:99]
	v_mfma_f32_16x16x32_bf16 v[96:99], v[162:165], v[210:213], v[96:99]
	v_mfma_f32_16x16x32_bf16 v[84:87], v[166:169], v[206:209], v[84:87]
	v_mfma_f32_16x16x32_bf16 v[84:87], v[170:173], v[210:213], v[84:87]
	v_mfma_f32_16x16x32_bf16 v[64:67], v[166:169], v[214:217], v[64:67]
	v_mfma_f32_16x16x32_bf16 v[64:67], v[170:173], v[218:221], v[64:67]
	v_mfma_f32_16x16x32_bf16 v[80:83], v[158:161], v[214:217], v[80:83]
	v_mfma_f32_16x16x32_bf16 v[80:83], v[162:165], v[218:221], v[80:83]
	v_mfma_f32_16x16x32_bf16 v[72:75], v[174:177], v[214:217], v[72:75]
	v_mfma_f32_16x16x32_bf16 v[72:75], v[178:181], v[218:221], v[72:75]
	v_mfma_f32_16x16x32_bf16 v[68:71], v[182:185], v[214:217], v[68:71]
	v_mfma_f32_16x16x32_bf16 v[68:71], v[186:189], v[218:221], v[68:71]
	v_mfma_f32_16x16x32_bf16 v[88:91], v[182:185], v[206:209], v[88:91]
	v_mfma_f32_16x16x32_bf16 v[88:91], v[186:189], v[210:213], v[88:91]
	v_mfma_f32_16x16x32_bf16 v[92:95], v[174:177], v[206:209], v[92:95]
	v_mfma_f32_16x16x32_bf16 v[92:95], v[178:181], v[210:213], v[92:95]
	v_mfma_f32_16x16x32_bf16 v[108:111], v[174:177], v[198:201], v[108:111]
	v_mfma_f32_16x16x32_bf16 v[108:111], v[178:181], v[202:205], v[108:111]
	v_mfma_f32_16x16x32_bf16 v[104:107], v[182:185], v[198:201], v[104:107]
	v_mfma_f32_16x16x32_bf16 v[104:107], v[186:189], v[202:205], v[104:107]
	v_mfma_f32_16x16x32_bf16 v[120:123], v[182:185], v[190:193], v[120:123]
	v_mfma_f32_16x16x32_bf16 v[120:123], v[186:189], v[194:197], v[120:123]
	v_mfma_f32_16x16x32_bf16 v[124:127], v[174:177], v[190:193], v[124:127]
	v_mfma_f32_16x16x32_bf16 v[124:127], v[178:181], v[194:197], v[124:127]
	s_barrier
	s_add_u32 s12, s56, 0x8000
	s_addc_u32 s13, s57, 0
	s_add_i32 s14, s14, s17
	v_lshl_add_u64 v[224:225], s[12:13], 0, v[134:135]
	s_mov_b32 m0, s14
	ds_read_b128 v[190:193], v155 offset:49152
	ds_read_b128 v[194:197], v155 offset:50176
	ds_read_b128 v[198:201], v155 offset:51200
	ds_read_b128 v[202:205], v155 offset:52224
	ds_read_b128 v[206:209], v155 offset:53248
	ds_read_b128 v[210:213], v155 offset:54272
	ds_read_b128 v[214:217], v155 offset:55296
	ds_read_b128 v[218:221], v155 offset:56320
	global_load_lds_dwordx4 v[224:225], off
	s_add_i32 m0, s14, 0x2000
	v_lshl_add_u64 v[224:225], s[12:13], 0, v[138:139]
	s_add_u32 s12, s56, 0xc000
	s_addc_u32 s13, s57, 0
	s_add_i32 s14, s68, s17
	global_load_lds_dwordx4 v[224:225], off
	v_lshl_add_u64 v[224:225], s[12:13], 0, v[134:135]
	s_mov_b32 m0, s14
	v_lshl_add_u64 v[144:145], v[144:145], 0, s[36:37]
	global_load_lds_dwordx4 v[224:225], off
	v_lshl_add_u64 v[224:225], s[12:13], 0, v[138:139]
	s_add_i32 m0, s14, 0x2000
	s_nop 0
	global_load_lds_dwordx4 v[224:225], off
	s_mov_b32 m0, s25
	s_nop 0
	global_load_lds_dwordx4 v[144:145], off
	v_lshl_add_u64 v[144:145], v[222:223], 0, s[36:37]
	s_mov_b32 m0, s33
	s_nop 0
	global_load_lds_dwordx4 v[144:145], off
	s_waitcnt vmcnt(8)
	s_waitcnt lgkmcnt(0)
	s_barrier
	v_mfma_f32_16x16x32_bf16 v[76:79], v[158:161], v[190:193], v[76:79]
	v_mfma_f32_16x16x32_bf16 v[76:79], v[162:165], v[194:197], v[76:79]
	v_mfma_f32_16x16x32_bf16 v[52:55], v[166:169], v[190:193], v[52:55]
	v_mfma_f32_16x16x32_bf16 v[52:55], v[170:173], v[194:197], v[52:55]
	v_mfma_f32_16x16x32_bf16 v[36:39], v[166:169], v[198:201], v[36:39]
	v_mfma_f32_16x16x32_bf16 v[36:39], v[170:173], v[202:205], v[36:39]
	v_mfma_f32_16x16x32_bf16 v[48:51], v[158:161], v[198:201], v[48:51]
	v_mfma_f32_16x16x32_bf16 v[48:51], v[162:165], v[202:205], v[48:51]
	v_mfma_f32_16x16x32_bf16 v[32:35], v[158:161], v[206:209], v[32:35]
	v_mfma_f32_16x16x32_bf16 v[32:35], v[162:165], v[210:213], v[32:35]
	v_mfma_f32_16x16x32_bf16 v[20:23], v[166:169], v[206:209], v[20:23]
	v_mfma_f32_16x16x32_bf16 v[20:23], v[170:173], v[210:213], v[20:23]
	v_mfma_f32_16x16x32_bf16 v[4:7], v[166:169], v[214:217], v[4:7]
	v_mfma_f32_16x16x32_bf16 v[4:7], v[170:173], v[218:221], v[4:7]
	v_mfma_f32_16x16x32_bf16 v[16:19], v[158:161], v[214:217], v[16:19]
	v_mfma_f32_16x16x32_bf16 v[16:19], v[162:165], v[218:221], v[16:19]
	v_mfma_f32_16x16x32_bf16 v[12:15], v[174:177], v[214:217], v[12:15]
	v_mfma_f32_16x16x32_bf16 v[12:15], v[178:181], v[218:221], v[12:15]
	v_mfma_f32_16x16x32_bf16 v[8:11], v[182:185], v[214:217], v[8:11]
	v_mfma_f32_16x16x32_bf16 v[8:11], v[186:189], v[218:221], v[8:11]
	v_mfma_f32_16x16x32_bf16 v[24:27], v[182:185], v[206:209], v[24:27]
	v_mfma_f32_16x16x32_bf16 v[24:27], v[186:189], v[210:213], v[24:27]
	v_mfma_f32_16x16x32_bf16 v[28:31], v[174:177], v[206:209], v[28:31]
	v_mfma_f32_16x16x32_bf16 v[28:31], v[178:181], v[210:213], v[28:31]
	v_mfma_f32_16x16x32_bf16 v[44:47], v[174:177], v[198:201], v[44:47]
	v_mfma_f32_16x16x32_bf16 v[44:47], v[178:181], v[202:205], v[44:47]
	v_mfma_f32_16x16x32_bf16 v[40:43], v[182:185], v[198:201], v[40:43]
	v_mfma_f32_16x16x32_bf16 v[40:43], v[186:189], v[202:205], v[40:43]
	v_mfma_f32_16x16x32_bf16 v[56:59], v[182:185], v[190:193], v[56:59]
	v_mfma_f32_16x16x32_bf16 v[56:59], v[186:189], v[194:197], v[56:59]
	v_mfma_f32_16x16x32_bf16 v[60:63], v[174:177], v[190:193], v[60:63]
	v_mfma_f32_16x16x32_bf16 v[60:63], v[178:181], v[194:197], v[60:63]
	s_barrier
	s_add_i32 s61, s61, 2
	s_add_u32 s62, s62, 0x10000
	s_addc_u32 s63, s63, 0
	s_add_u32 s64, s64, 0x100
	s_addc_u32 s65, s65, 0
	s_add_u32 s8, s8, 0xffffff00
	s_addc_u32 s9, s9, -1
	v_lshl_add_u64 v[2:3], v[2:3], 0, s[40:41]
	s_cmp_gt_u32 s61, 61
	v_lshl_add_u64 v[148:149], v[148:149], 0, s[40:41]
	s_cbranch_scc0 .LBB0_510
	s_and_b64 vcc, exec, s[38:39]
	s_cbranch_vccz .LBB0_513
	s_barrier

.LBB0_668:
	ds_read_b128 v[158:161], v155
	ds_read_b128 v[162:165], v155 offset:1024
	ds_read_b128 v[166:169], v155 offset:2048
	ds_read_b128 v[170:173], v155 offset:3072
	ds_read_b128 v[174:177], v156
	ds_read_b128 v[178:181], v156 offset:1024
	ds_read_b128 v[182:185], v156 offset:2048
	ds_read_b128 v[186:189], v156 offset:3072
	s_add_u32 s12, s70, s34
	s_addc_u32 s13, s71, 0
	s_cmp_eq_u32 s34, s6
	s_cselect_b32 s23, s0, s13
	s_cselect_b32 s22, s1, s12
	s_cselect_b32 s55, s43, s69
	s_cselect_b32 s54, s66, s68
	s_add_i32 s73, s21, 0xc000
	v_lshl_add_u64 v[144:145], v[2:3], 0, s[34:35]
	s_mov_b32 m0, s73
	s_add_i32 s72, s21, 0xe000
	ds_read_b128 v[190:193], v157
	ds_read_b128 v[194:197], v157 offset:1024
	ds_read_b128 v[198:201], v157 offset:2048
	ds_read_b128 v[202:205], v157 offset:3072
	ds_read_b128 v[206:209], v157 offset:4096
	ds_read_b128 v[210:213], v157 offset:5120
	ds_read_b128 v[214:217], v157 offset:6144
	ds_read_b128 v[218:221], v157 offset:7168
	global_load_lds_dwordx4 v[144:145], off
	v_lshl_add_u64 v[144:145], v[148:149], 0, s[34:35]
	s_mov_b32 m0, s72
	s_nop 0
	global_load_lds_dwordx4 v[144:145], off
	s_waitcnt vmcnt(8)
	s_waitcnt lgkmcnt(0)
	s_barrier
	v_mfma_f32_16x16x32_bf16 v[120:123], v[158:161], v[190:193], v[120:123]
	v_mfma_f32_16x16x32_bf16 v[120:123], v[162:165], v[194:197], v[120:123]
	v_mfma_f32_16x16x32_bf16 v[116:119], v[166:169], v[190:193], v[116:119]
	v_mfma_f32_16x16x32_bf16 v[116:119], v[170:173], v[194:197], v[116:119]
	v_mfma_f32_16x16x32_bf16 v[100:103], v[166:169], v[198:201], v[100:103]
	v_mfma_f32_16x16x32_bf16 v[100:103], v[170:173], v[202:205], v[100:103]
	v_mfma_f32_16x16x32_bf16 v[104:107], v[158:161], v[198:201], v[104:107]
	v_mfma_f32_16x16x32_bf16 v[104:107], v[162:165], v[202:205], v[104:107]
	v_mfma_f32_16x16x32_bf16 v[88:91], v[158:161], v[206:209], v[88:91]
	v_mfma_f32_16x16x32_bf16 v[88:91], v[162:165], v[210:213], v[88:91]
	v_mfma_f32_16x16x32_bf16 v[84:87], v[166:169], v[206:209], v[84:87]
	v_mfma_f32_16x16x32_bf16 v[84:87], v[170:173], v[210:213], v[84:87]
	v_mfma_f32_16x16x32_bf16 v[68:71], v[166:169], v[214:217], v[68:71]
	v_mfma_f32_16x16x32_bf16 v[68:71], v[170:173], v[218:221], v[68:71]
	v_mfma_f32_16x16x32_bf16 v[72:75], v[158:161], v[214:217], v[72:75]
	v_mfma_f32_16x16x32_bf16 v[72:75], v[162:165], v[218:221], v[72:75]
	v_mfma_f32_16x16x32_bf16 v[80:83], v[174:177], v[214:217], v[80:83]
	v_mfma_f32_16x16x32_bf16 v[80:83], v[178:181], v[218:221], v[80:83]
	v_mfma_f32_16x16x32_bf16 v[76:79], v[182:185], v[214:217], v[76:79]
	v_mfma_f32_16x16x32_bf16 v[76:79], v[186:189], v[218:221], v[76:79]
	v_mfma_f32_16x16x32_bf16 v[92:95], v[182:185], v[206:209], v[92:95]
	v_mfma_f32_16x16x32_bf16 v[92:95], v[186:189], v[210:213], v[92:95]
	v_mfma_f32_16x16x32_bf16 v[96:99], v[174:177], v[206:209], v[96:99]
	v_mfma_f32_16x16x32_bf16 v[96:99], v[178:181], v[210:213], v[96:99]
	v_mfma_f32_16x16x32_bf16 v[112:115], v[174:177], v[198:201], v[112:115]
	v_mfma_f32_16x16x32_bf16 v[112:115], v[178:181], v[202:205], v[112:115]
	v_mfma_f32_16x16x32_bf16 v[108:111], v[182:185], v[198:201], v[108:111]
	v_mfma_f32_16x16x32_bf16 v[108:111], v[186:189], v[202:205], v[108:111]
	v_mfma_f32_16x16x32_bf16 v[124:127], v[182:185], v[190:193], v[124:127]
	v_mfma_f32_16x16x32_bf16 v[124:127], v[186:189], v[194:197], v[124:127]
	v_mfma_f32_16x16x32_bf16 v[128:131], v[174:177], v[190:193], v[128:131]
	v_mfma_f32_16x16x32_bf16 v[128:131], v[178:181], v[194:197], v[128:131]
	s_barrier
	s_add_i32 s12, s58, s20
	v_lshl_add_u64 v[144:145], s[54:55], 0, v[134:135]
	s_mov_b32 m0, s12
	ds_read_b128 v[190:193], v157 offset:16384
	ds_read_b128 v[194:197], v157 offset:17408
	ds_read_b128 v[198:201], v157 offset:18432
	ds_read_b128 v[202:205], v157 offset:19456
	ds_read_b128 v[206:209], v157 offset:20480
	ds_read_b128 v[210:213], v157 offset:21504
	ds_read_b128 v[214:217], v157 offset:22528
	ds_read_b128 v[218:221], v157 offset:23552
	global_load_lds_dwordx4 v[144:145], off
	s_add_i32 m0, s12, 0x2000
	s_add_u32 s12, s54, 0x4000
	v_lshl_add_u64 v[144:145], s[54:55], 0, v[138:139]
	s_addc_u32 s13, s55, 0
	s_add_i32 s14, s59, s20
	global_load_lds_dwordx4 v[144:145], off
	v_lshl_add_u64 v[144:145], s[12:13], 0, v[134:135]
	s_mov_b32 m0, s14
	v_lshl_add_u64 v[222:223], s[22:23], 0, v[136:137]
	global_load_lds_dwordx4 v[144:145], off
	v_lshl_add_u64 v[144:145], s[12:13], 0, v[138:139]
	s_add_i32 m0, s14, 0x2000
	s_nop 0
	global_load_lds_dwordx4 v[144:145], off
	v_lshl_add_u64 v[144:145], s[22:23], 0, v[132:133]
	s_mov_b32 m0, s21
	s_nop 0
	global_load_lds_dwordx4 v[144:145], off
	s_mov_b32 m0, s24
	s_nop 0
	global_load_lds_dwordx4 v[222:223], off
	s_waitcnt vmcnt(8)
	s_waitcnt lgkmcnt(0)
	s_barrier
	v_mfma_f32_16x16x32_bf16 v[56:59], v[158:161], v[190:193], v[56:59]
	v_mfma_f32_16x16x32_bf16 v[56:59], v[162:165], v[194:197], v[56:59]
	v_mfma_f32_16x16x32_bf16 v[52:55], v[166:169], v[190:193], v[52:55]
	v_mfma_f32_16x16x32_bf16 v[52:55], v[170:173], v[194:197], v[52:55]
	v_mfma_f32_16x16x32_bf16 v[36:39], v[166:169], v[198:201], v[36:39]
	v_mfma_f32_16x16x32_bf16 v[36:39], v[170:173], v[202:205], v[36:39]
	v_mfma_f32_16x16x32_bf16 v[40:43], v[158:161], v[198:201], v[40:43]
	v_mfma_f32_16x16x32_bf16 v[40:43], v[162:165], v[202:205], v[40:43]
	v_mfma_f32_16x16x32_bf16 v[24:27], v[158:161], v[206:209], v[24:27]
	v_mfma_f32_16x16x32_bf16 v[24:27], v[162:165], v[210:213], v[24:27]
	v_mfma_f32_16x16x32_bf16 v[20:23], v[166:169], v[206:209], v[20:23]
	v_mfma_f32_16x16x32_bf16 v[20:23], v[170:173], v[210:213], v[20:23]
	v_mfma_f32_16x16x32_bf16 v[4:7], v[166:169], v[214:217], v[4:7]
	v_mfma_f32_16x16x32_bf16 v[4:7], v[170:173], v[218:221], v[4:7]
	v_mfma_f32_16x16x32_bf16 v[8:11], v[158:161], v[214:217], v[8:11]
	v_mfma_f32_16x16x32_bf16 v[8:11], v[162:165], v[218:221], v[8:11]
	v_mfma_f32_16x16x32_bf16 v[16:19], v[174:177], v[214:217], v[16:19]
	v_mfma_f32_16x16x32_bf16 v[16:19], v[178:181], v[218:221], v[16:19]
	v_mfma_f32_16x16x32_bf16 v[12:15], v[182:185], v[214:217], v[12:15]
	v_mfma_f32_16x16x32_bf16 v[12:15], v[186:189], v[218:221], v[12:15]
	v_mfma_f32_16x16x32_bf16 v[28:31], v[182:185], v[206:209], v[28:31]
	v_mfma_f32_16x16x32_bf16 v[28:31], v[186:189], v[210:213], v[28:31]
	v_mfma_f32_16x16x32_bf16 v[32:35], v[174:177], v[206:209], v[32:35]
	v_mfma_f32_16x16x32_bf16 v[32:35], v[178:181], v[210:213], v[32:35]
	v_mfma_f32_16x16x32_bf16 v[48:51], v[174:177], v[198:201], v[48:51]
	v_mfma_f32_16x16x32_bf16 v[48:51], v[178:181], v[202:205], v[48:51]
	v_mfma_f32_16x16x32_bf16 v[44:47], v[182:185], v[198:201], v[44:47]
	v_mfma_f32_16x16x32_bf16 v[44:47], v[186:189], v[202:205], v[44:47]
	v_mfma_f32_16x16x32_bf16 v[60:63], v[182:185], v[190:193], v[60:63]
	v_mfma_f32_16x16x32_bf16 v[60:63], v[186:189], v[194:197], v[60:63]
	v_mfma_f32_16x16x32_bf16 v[64:67], v[174:177], v[190:193], v[64:67]
	v_mfma_f32_16x16x32_bf16 v[64:67], v[178:181], v[194:197], v[64:67]
	s_barrier
	s_add_i32 s14, 0, 0x18000
	v_add_u32_e32 v1, s14, v152
	s_add_i32 s74, 0, 0x1c000
	ds_read_b128 v[158:161], v1
	ds_read_b128 v[162:165], v1 offset:1024
	ds_read_b128 v[166:169], v1 offset:2048
	ds_read_b128 v[170:173], v1 offset:3072
	v_add_u32_e32 v1, s74, v152
	ds_read_b128 v[174:177], v1
	ds_read_b128 v[178:181], v1 offset:1024
	ds_read_b128 v[182:185], v1 offset:2048
	ds_read_b128 v[186:189], v1 offset:3072
	s_add_u32 s12, s22, 0x100000
	s_addc_u32 s13, s23, 0
	s_mov_b32 m0, s25
	v_lshl_add_u64 v[224:225], s[12:13], 0, v[132:133]
	ds_read_b128 v[190:193], v157 offset:32768
	ds_read_b128 v[194:197], v157 offset:33792
	ds_read_b128 v[198:201], v157 offset:34816
	ds_read_b128 v[202:205], v157 offset:35840
	ds_read_b128 v[206:209], v157 offset:36864
	ds_read_b128 v[210:213], v157 offset:37888
	ds_read_b128 v[214:217], v157 offset:38912
	ds_read_b128 v[218:221], v157 offset:39936
	global_load_lds_dwordx4 v[224:225], off
	v_lshl_add_u64 v[224:225], s[12:13], 0, v[136:137]
	s_mov_b32 m0, s33
	s_nop 0
	global_load_lds_dwordx4 v[224:225], off
	s_waitcnt vmcnt(8)
	s_waitcnt lgkmcnt(0)
	s_barrier
	v_mfma_f32_16x16x32_bf16 v[120:123], v[158:161], v[190:193], v[120:123]
	v_mfma_f32_16x16x32_bf16 v[120:123], v[162:165], v[194:197], v[120:123]
	v_mfma_f32_16x16x32_bf16 v[116:119], v[166:169], v[190:193], v[116:119]
	v_mfma_f32_16x16x32_bf16 v[116:119], v[170:173], v[194:197], v[116:119]
	v_mfma_f32_16x16x32_bf16 v[100:103], v[166:169], v[198:201], v[100:103]
	v_mfma_f32_16x16x32_bf16 v[100:103], v[170:173], v[202:205], v[100:103]
	v_mfma_f32_16x16x32_bf16 v[104:107], v[158:161], v[198:201], v[104:107]
	v_mfma_f32_16x16x32_bf16 v[104:107], v[162:165], v[202:205], v[104:107]
	v_mfma_f32_16x16x32_bf16 v[88:91], v[158:161], v[206:209], v[88:91]
	v_mfma_f32_16x16x32_bf16 v[88:91], v[162:165], v[210:213], v[88:91]
	v_mfma_f32_16x16x32_bf16 v[84:87], v[166:169], v[206:209], v[84:87]
	v_mfma_f32_16x16x32_bf16 v[84:87], v[170:173], v[210:213], v[84:87]
	v_mfma_f32_16x16x32_bf16 v[68:71], v[166:169], v[214:217], v[68:71]
	v_mfma_f32_16x16x32_bf16 v[68:71], v[170:173], v[218:221], v[68:71]
	v_mfma_f32_16x16x32_bf16 v[72:75], v[158:161], v[214:217], v[72:75]
	v_mfma_f32_16x16x32_bf16 v[72:75], v[162:165], v[218:221], v[72:75]
	v_mfma_f32_16x16x32_bf16 v[80:83], v[174:177], v[214:217], v[80:83]
	v_mfma_f32_16x16x32_bf16 v[80:83], v[178:181], v[218:221], v[80:83]
	v_mfma_f32_16x16x32_bf16 v[76:79], v[182:185], v[214:217], v[76:79]
	v_mfma_f32_16x16x32_bf16 v[76:79], v[186:189], v[218:221], v[76:79]
	v_mfma_f32_16x16x32_bf16 v[92:95], v[182:185], v[206:209], v[92:95]
	v_mfma_f32_16x16x32_bf16 v[92:95], v[186:189], v[210:213], v[92:95]
	v_mfma_f32_16x16x32_bf16 v[96:99], v[174:177], v[206:209], v[96:99]
	v_mfma_f32_16x16x32_bf16 v[96:99], v[178:181], v[210:213], v[96:99]
	v_mfma_f32_16x16x32_bf16 v[112:115], v[174:177], v[198:201], v[112:115]
	v_mfma_f32_16x16x32_bf16 v[112:115], v[178:181], v[202:205], v[112:115]
	v_mfma_f32_16x16x32_bf16 v[108:111], v[182:185], v[198:201], v[108:111]
	v_mfma_f32_16x16x32_bf16 v[108:111], v[186:189], v[202:205], v[108:111]
	v_mfma_f32_16x16x32_bf16 v[124:127], v[182:185], v[190:193], v[124:127]
	v_mfma_f32_16x16x32_bf16 v[124:127], v[186:189], v[194:197], v[124:127]
	v_mfma_f32_16x16x32_bf16 v[128:131], v[174:177], v[190:193], v[128:131]
	v_mfma_f32_16x16x32_bf16 v[128:131], v[178:181], v[194:197], v[128:131]
	s_barrier
	s_add_u32 s12, s54, 0x8000
	s_addc_u32 s13, s55, 0
	s_add_i32 s14, s14, s20
	v_lshl_add_u64 v[224:225], s[12:13], 0, v[134:135]
	s_mov_b32 m0, s14
	ds_read_b128 v[190:193], v157 offset:49152
	ds_read_b128 v[194:197], v157 offset:50176
	ds_read_b128 v[198:201], v157 offset:51200
	ds_read_b128 v[202:205], v157 offset:52224
	ds_read_b128 v[206:209], v157 offset:53248
	ds_read_b128 v[210:213], v157 offset:54272
	ds_read_b128 v[214:217], v157 offset:55296
	ds_read_b128 v[218:221], v157 offset:56320
	global_load_lds_dwordx4 v[224:225], off
	s_add_i32 m0, s14, 0x2000
	v_lshl_add_u64 v[224:225], s[12:13], 0, v[138:139]
	s_add_u32 s12, s54, 0xc000
	s_addc_u32 s13, s55, 0
	s_add_i32 s14, s74, s20
	global_load_lds_dwordx4 v[224:225], off
	v_lshl_add_u64 v[224:225], s[12:13], 0, v[134:135]
	s_mov_b32 m0, s14
	v_lshl_add_u64 v[144:145], v[144:145], 0, s[30:31]
	global_load_lds_dwordx4 v[224:225], off
	v_lshl_add_u64 v[224:225], s[12:13], 0, v[138:139]
	s_add_i32 m0, s14, 0x2000
	s_nop 0
	global_load_lds_dwordx4 v[224:225], off
	s_mov_b32 m0, s51
	s_nop 0
	global_load_lds_dwordx4 v[144:145], off
	v_lshl_add_u64 v[144:145], v[222:223], 0, s[30:31]
	s_mov_b32 m0, s53
	s_nop 0
	global_load_lds_dwordx4 v[144:145], off
	s_waitcnt vmcnt(8)
	s_waitcnt lgkmcnt(0)
	s_barrier
	v_mfma_f32_16x16x32_bf16 v[56:59], v[158:161], v[190:193], v[56:59]
	v_mfma_f32_16x16x32_bf16 v[56:59], v[162:165], v[194:197], v[56:59]
	v_mfma_f32_16x16x32_bf16 v[52:55], v[166:169], v[190:193], v[52:55]
	v_mfma_f32_16x16x32_bf16 v[52:55], v[170:173], v[194:197], v[52:55]
	v_mfma_f32_16x16x32_bf16 v[36:39], v[166:169], v[198:201], v[36:39]
	v_mfma_f32_16x16x32_bf16 v[36:39], v[170:173], v[202:205], v[36:39]
	v_mfma_f32_16x16x32_bf16 v[40:43], v[158:161], v[198:201], v[40:43]
	v_mfma_f32_16x16x32_bf16 v[40:43], v[162:165], v[202:205], v[40:43]
	v_mfma_f32_16x16x32_bf16 v[24:27], v[158:161], v[206:209], v[24:27]
	v_mfma_f32_16x16x32_bf16 v[24:27], v[162:165], v[210:213], v[24:27]
	v_mfma_f32_16x16x32_bf16 v[20:23], v[166:169], v[206:209], v[20:23]
	v_mfma_f32_16x16x32_bf16 v[20:23], v[170:173], v[210:213], v[20:23]
	v_mfma_f32_16x16x32_bf16 v[4:7], v[166:169], v[214:217], v[4:7]
	v_mfma_f32_16x16x32_bf16 v[4:7], v[170:173], v[218:221], v[4:7]
	v_mfma_f32_16x16x32_bf16 v[8:11], v[158:161], v[214:217], v[8:11]
	v_mfma_f32_16x16x32_bf16 v[8:11], v[162:165], v[218:221], v[8:11]
	v_mfma_f32_16x16x32_bf16 v[16:19], v[174:177], v[214:217], v[16:19]
	v_mfma_f32_16x16x32_bf16 v[16:19], v[178:181], v[218:221], v[16:19]
	v_mfma_f32_16x16x32_bf16 v[12:15], v[182:185], v[214:217], v[12:15]
	v_mfma_f32_16x16x32_bf16 v[12:15], v[186:189], v[218:221], v[12:15]
	v_mfma_f32_16x16x32_bf16 v[28:31], v[182:185], v[206:209], v[28:31]
	v_mfma_f32_16x16x32_bf16 v[28:31], v[186:189], v[210:213], v[28:31]
	v_mfma_f32_16x16x32_bf16 v[32:35], v[174:177], v[206:209], v[32:35]
	v_mfma_f32_16x16x32_bf16 v[32:35], v[178:181], v[210:213], v[32:35]
	v_mfma_f32_16x16x32_bf16 v[48:51], v[174:177], v[198:201], v[48:51]
	v_mfma_f32_16x16x32_bf16 v[48:51], v[178:181], v[202:205], v[48:51]
	v_mfma_f32_16x16x32_bf16 v[44:47], v[182:185], v[198:201], v[44:47]
	v_mfma_f32_16x16x32_bf16 v[44:47], v[186:189], v[202:205], v[44:47]
	v_mfma_f32_16x16x32_bf16 v[60:63], v[182:185], v[190:193], v[60:63]
	v_mfma_f32_16x16x32_bf16 v[60:63], v[186:189], v[194:197], v[60:63]
	v_mfma_f32_16x16x32_bf16 v[64:67], v[174:177], v[190:193], v[64:67]
	v_mfma_f32_16x16x32_bf16 v[64:67], v[178:181], v[194:197], v[64:67]
	s_barrier
	s_add_i32 s67, s67, 2
	s_add_u32 s68, s68, 0x10000
	s_addc_u32 s69, s69, 0
	s_add_u32 s70, s70, 0x100
	s_addc_u32 s71, s71, 0
	s_add_u32 s6, s6, 0xffffff00
	s_addc_u32 s7, s7, -1
	v_lshl_add_u64 v[2:3], v[2:3], 0, s[38:39]
	s_cmp_gt_u32 s67, 61
	v_lshl_add_u64 v[148:149], v[148:149], 0, s[38:39]
	s_cbranch_scc0 .LBB0_668
	s_and_b64 vcc, exec, s[36:37]
	s_cbranch_vccnz .LBB0_676
	s_and_b64 s[0:1], s[10:11], s[4:5]
	s_andn2_b64 vcc, exec, s[0:1]
	s_cbranch_vccz .LBB0_677

.LBB0_762:
	ds_read_b128 v[158:161], v153
	ds_read_b128 v[162:165], v153 offset:1024
	ds_read_b128 v[166:169], v153 offset:2048
	ds_read_b128 v[170:173], v153 offset:3072
	ds_read_b128 v[174:177], v154
	ds_read_b128 v[178:181], v154 offset:1024
	ds_read_b128 v[182:185], v154 offset:2048
	ds_read_b128 v[186:189], v154 offset:3072
	s_add_u32 s12, s65, s30
	s_addc_u32 s13, s66, 0
	s_cmp_eq_u32 s30, s50
	s_cselect_b32 s23, s11, s13
	s_cselect_b32 s22, s10, s12
	s_cselect_b32 s53, s49, s64
	s_cselect_b32 s52, s48, s1
	s_add_i32 s68, s19, 0xc000
	v_lshl_add_u64 v[144:145], v[2:3], 0, s[30:31]
	s_mov_b32 m0, s68
	s_add_i32 s67, s19, 0xe000
	ds_read_b128 v[190:193], v155
	ds_read_b128 v[194:197], v155 offset:1024
	ds_read_b128 v[198:201], v155 offset:2048
	ds_read_b128 v[202:205], v155 offset:3072
	ds_read_b128 v[206:209], v155 offset:4096
	ds_read_b128 v[210:213], v155 offset:5120
	ds_read_b128 v[214:217], v155 offset:6144
	ds_read_b128 v[218:221], v155 offset:7168
	global_load_lds_dwordx4 v[144:145], off
	v_lshl_add_u64 v[144:145], v[148:149], 0, s[30:31]
	s_mov_b32 m0, s67
	s_nop 0
	global_load_lds_dwordx4 v[144:145], off
	s_waitcnt vmcnt(8)
	s_waitcnt lgkmcnt(0)
	s_barrier
	v_mfma_f32_16x16x32_bf16 v[128:131], v[158:161], v[190:193], v[128:131]
	v_mfma_f32_16x16x32_bf16 v[128:131], v[162:165], v[194:197], v[128:131]
	v_mfma_f32_16x16x32_bf16 v[116:119], v[166:169], v[190:193], v[116:119]
	v_mfma_f32_16x16x32_bf16 v[116:119], v[170:173], v[194:197], v[116:119]
	v_mfma_f32_16x16x32_bf16 v[100:103], v[166:169], v[198:201], v[100:103]
	v_mfma_f32_16x16x32_bf16 v[100:103], v[170:173], v[202:205], v[100:103]
	v_mfma_f32_16x16x32_bf16 v[112:115], v[158:161], v[198:201], v[112:115]
	v_mfma_f32_16x16x32_bf16 v[112:115], v[162:165], v[202:205], v[112:115]
	v_mfma_f32_16x16x32_bf16 v[96:99], v[158:161], v[206:209], v[96:99]
	v_mfma_f32_16x16x32_bf16 v[96:99], v[162:165], v[210:213], v[96:99]
	v_mfma_f32_16x16x32_bf16 v[84:87], v[166:169], v[206:209], v[84:87]
	v_mfma_f32_16x16x32_bf16 v[84:87], v[170:173], v[210:213], v[84:87]
	v_mfma_f32_16x16x32_bf16 v[64:67], v[166:169], v[214:217], v[64:67]
	v_mfma_f32_16x16x32_bf16 v[64:67], v[170:173], v[218:221], v[64:67]
	v_mfma_f32_16x16x32_bf16 v[80:83], v[158:161], v[214:217], v[80:83]
	v_mfma_f32_16x16x32_bf16 v[80:83], v[162:165], v[218:221], v[80:83]
	v_mfma_f32_16x16x32_bf16 v[72:75], v[174:177], v[214:217], v[72:75]
	v_mfma_f32_16x16x32_bf16 v[72:75], v[178:181], v[218:221], v[72:75]
	v_mfma_f32_16x16x32_bf16 v[68:71], v[182:185], v[214:217], v[68:71]
	v_mfma_f32_16x16x32_bf16 v[68:71], v[186:189], v[218:221], v[68:71]
	v_mfma_f32_16x16x32_bf16 v[88:91], v[182:185], v[206:209], v[88:91]
	v_mfma_f32_16x16x32_bf16 v[88:91], v[186:189], v[210:213], v[88:91]
	v_mfma_f32_16x16x32_bf16 v[92:95], v[174:177], v[206:209], v[92:95]
	v_mfma_f32_16x16x32_bf16 v[92:95], v[178:181], v[210:213], v[92:95]
	v_mfma_f32_16x16x32_bf16 v[108:111], v[174:177], v[198:201], v[108:111]
	v_mfma_f32_16x16x32_bf16 v[108:111], v[178:181], v[202:205], v[108:111]
	v_mfma_f32_16x16x32_bf16 v[104:107], v[182:185], v[198:201], v[104:107]
	v_mfma_f32_16x16x32_bf16 v[104:107], v[186:189], v[202:205], v[104:107]
	v_mfma_f32_16x16x32_bf16 v[120:123], v[182:185], v[190:193], v[120:123]
	v_mfma_f32_16x16x32_bf16 v[120:123], v[186:189], v[194:197], v[120:123]
	v_mfma_f32_16x16x32_bf16 v[124:127], v[174:177], v[190:193], v[124:127]
	v_mfma_f32_16x16x32_bf16 v[124:127], v[178:181], v[194:197], v[124:127]
	s_barrier
	s_add_i32 s12, s57, s2
	v_lshl_add_u64 v[144:145], s[52:53], 0, v[134:135]
	s_mov_b32 m0, s12
	ds_read_b128 v[190:193], v155 offset:16384
	ds_read_b128 v[194:197], v155 offset:17408
	ds_read_b128 v[198:201], v155 offset:18432
	ds_read_b128 v[202:205], v155 offset:19456
	ds_read_b128 v[206:209], v155 offset:20480
	ds_read_b128 v[210:213], v155 offset:21504
	ds_read_b128 v[214:217], v155 offset:22528
	ds_read_b128 v[218:221], v155 offset:23552
	global_load_lds_dwordx4 v[144:145], off
	s_add_i32 m0, s12, 0x2000
	s_add_u32 s12, s52, 0x4000
	v_lshl_add_u64 v[144:145], s[52:53], 0, v[138:139]
	s_addc_u32 s13, s53, 0
	s_add_i32 s14, s58, s2
	global_load_lds_dwordx4 v[144:145], off
	v_lshl_add_u64 v[144:145], s[12:13], 0, v[134:135]
	s_mov_b32 m0, s14
	v_lshl_add_u64 v[222:223], s[22:23], 0, v[136:137]
	global_load_lds_dwordx4 v[144:145], off
	v_lshl_add_u64 v[144:145], s[12:13], 0, v[138:139]
	s_add_i32 m0, s14, 0x2000
	s_nop 0
	global_load_lds_dwordx4 v[144:145], off
	v_lshl_add_u64 v[144:145], s[22:23], 0, v[132:133]
	s_mov_b32 m0, s19
	s_nop 0
	global_load_lds_dwordx4 v[144:145], off
	s_mov_b32 m0, s20
	s_nop 0
	global_load_lds_dwordx4 v[222:223], off
	s_waitcnt vmcnt(8)
	s_waitcnt lgkmcnt(0)
	s_barrier
	v_mfma_f32_16x16x32_bf16 v[76:79], v[158:161], v[190:193], v[76:79]
	v_mfma_f32_16x16x32_bf16 v[76:79], v[162:165], v[194:197], v[76:79]
	v_mfma_f32_16x16x32_bf16 v[52:55], v[166:169], v[190:193], v[52:55]
	v_mfma_f32_16x16x32_bf16 v[52:55], v[170:173], v[194:197], v[52:55]
	v_mfma_f32_16x16x32_bf16 v[36:39], v[166:169], v[198:201], v[36:39]
	v_mfma_f32_16x16x32_bf16 v[36:39], v[170:173], v[202:205], v[36:39]
	v_mfma_f32_16x16x32_bf16 v[48:51], v[158:161], v[198:201], v[48:51]
	v_mfma_f32_16x16x32_bf16 v[48:51], v[162:165], v[202:205], v[48:51]
	v_mfma_f32_16x16x32_bf16 v[32:35], v[158:161], v[206:209], v[32:35]
	v_mfma_f32_16x16x32_bf16 v[32:35], v[162:165], v[210:213], v[32:35]
	v_mfma_f32_16x16x32_bf16 v[20:23], v[166:169], v[206:209], v[20:23]
	v_mfma_f32_16x16x32_bf16 v[20:23], v[170:173], v[210:213], v[20:23]
	v_mfma_f32_16x16x32_bf16 v[4:7], v[166:169], v[214:217], v[4:7]
	v_mfma_f32_16x16x32_bf16 v[4:7], v[170:173], v[218:221], v[4:7]
	v_mfma_f32_16x16x32_bf16 v[16:19], v[158:161], v[214:217], v[16:19]
	v_mfma_f32_16x16x32_bf16 v[16:19], v[162:165], v[218:221], v[16:19]
	v_mfma_f32_16x16x32_bf16 v[12:15], v[174:177], v[214:217], v[12:15]
	v_mfma_f32_16x16x32_bf16 v[12:15], v[178:181], v[218:221], v[12:15]
	v_mfma_f32_16x16x32_bf16 v[8:11], v[182:185], v[214:217], v[8:11]
	v_mfma_f32_16x16x32_bf16 v[8:11], v[186:189], v[218:221], v[8:11]
	v_mfma_f32_16x16x32_bf16 v[24:27], v[182:185], v[206:209], v[24:27]
	v_mfma_f32_16x16x32_bf16 v[24:27], v[186:189], v[210:213], v[24:27]
	v_mfma_f32_16x16x32_bf16 v[28:31], v[174:177], v[206:209], v[28:31]
	v_mfma_f32_16x16x32_bf16 v[28:31], v[178:181], v[210:213], v[28:31]
	v_mfma_f32_16x16x32_bf16 v[44:47], v[174:177], v[198:201], v[44:47]
	v_mfma_f32_16x16x32_bf16 v[44:47], v[178:181], v[202:205], v[44:47]
	v_mfma_f32_16x16x32_bf16 v[40:43], v[182:185], v[198:201], v[40:43]
	v_mfma_f32_16x16x32_bf16 v[40:43], v[186:189], v[202:205], v[40:43]
	v_mfma_f32_16x16x32_bf16 v[56:59], v[182:185], v[190:193], v[56:59]
	v_mfma_f32_16x16x32_bf16 v[56:59], v[186:189], v[194:197], v[56:59]
	v_mfma_f32_16x16x32_bf16 v[60:63], v[174:177], v[190:193], v[60:63]
	v_mfma_f32_16x16x32_bf16 v[60:63], v[178:181], v[194:197], v[60:63]
	s_barrier
	s_add_i32 s14, 0, 0x18000
	v_add_u32_e32 v1, s14, v151
	s_add_i32 s69, 0, 0x1c000
	ds_read_b128 v[158:161], v1
	ds_read_b128 v[162:165], v1 offset:1024
	ds_read_b128 v[166:169], v1 offset:2048
	ds_read_b128 v[170:173], v1 offset:3072
	v_add_u32_e32 v1, s69, v151
	ds_read_b128 v[174:177], v1
	ds_read_b128 v[178:181], v1 offset:1024
	ds_read_b128 v[182:185], v1 offset:2048
	ds_read_b128 v[186:189], v1 offset:3072
	s_add_u32 s12, s22, 0x2b0000
	s_addc_u32 s13, s23, 0
	s_mov_b32 m0, s21
	v_lshl_add_u64 v[224:225], s[12:13], 0, v[132:133]
	ds_read_b128 v[190:193], v155 offset:32768
	ds_read_b128 v[194:197], v155 offset:33792
	ds_read_b128 v[198:201], v155 offset:34816
	ds_read_b128 v[202:205], v155 offset:35840
	ds_read_b128 v[206:209], v155 offset:36864
	ds_read_b128 v[210:213], v155 offset:37888
	ds_read_b128 v[214:217], v155 offset:38912
	ds_read_b128 v[218:221], v155 offset:39936
	global_load_lds_dwordx4 v[224:225], off
	v_lshl_add_u64 v[224:225], s[12:13], 0, v[136:137]
	s_mov_b32 m0, s24
	s_nop 0
	global_load_lds_dwordx4 v[224:225], off
	s_waitcnt vmcnt(8)
	s_waitcnt lgkmcnt(0)
	s_barrier
	v_mfma_f32_16x16x32_bf16 v[128:131], v[158:161], v[190:193], v[128:131]
	v_mfma_f32_16x16x32_bf16 v[128:131], v[162:165], v[194:197], v[128:131]
	v_mfma_f32_16x16x32_bf16 v[116:119], v[166:169], v[190:193], v[116:119]
	v_mfma_f32_16x16x32_bf16 v[116:119], v[170:173], v[194:197], v[116:119]
	v_mfma_f32_16x16x32_bf16 v[100:103], v[166:169], v[198:201], v[100:103]
	v_mfma_f32_16x16x32_bf16 v[100:103], v[170:173], v[202:205], v[100:103]
	v_mfma_f32_16x16x32_bf16 v[112:115], v[158:161], v[198:201], v[112:115]
	v_mfma_f32_16x16x32_bf16 v[112:115], v[162:165], v[202:205], v[112:115]
	v_mfma_f32_16x16x32_bf16 v[96:99], v[158:161], v[206:209], v[96:99]
	v_mfma_f32_16x16x32_bf16 v[96:99], v[162:165], v[210:213], v[96:99]
	v_mfma_f32_16x16x32_bf16 v[84:87], v[166:169], v[206:209], v[84:87]
	v_mfma_f32_16x16x32_bf16 v[84:87], v[170:173], v[210:213], v[84:87]
	v_mfma_f32_16x16x32_bf16 v[64:67], v[166:169], v[214:217], v[64:67]
	v_mfma_f32_16x16x32_bf16 v[64:67], v[170:173], v[218:221], v[64:67]
	v_mfma_f32_16x16x32_bf16 v[80:83], v[158:161], v[214:217], v[80:83]
	v_mfma_f32_16x16x32_bf16 v[80:83], v[162:165], v[218:221], v[80:83]
	v_mfma_f32_16x16x32_bf16 v[72:75], v[174:177], v[214:217], v[72:75]
	v_mfma_f32_16x16x32_bf16 v[72:75], v[178:181], v[218:221], v[72:75]
	v_mfma_f32_16x16x32_bf16 v[68:71], v[182:185], v[214:217], v[68:71]
	v_mfma_f32_16x16x32_bf16 v[68:71], v[186:189], v[218:221], v[68:71]
	v_mfma_f32_16x16x32_bf16 v[88:91], v[182:185], v[206:209], v[88:91]
	v_mfma_f32_16x16x32_bf16 v[88:91], v[186:189], v[210:213], v[88:91]
	v_mfma_f32_16x16x32_bf16 v[92:95], v[174:177], v[206:209], v[92:95]
	v_mfma_f32_16x16x32_bf16 v[92:95], v[178:181], v[210:213], v[92:95]
	v_mfma_f32_16x16x32_bf16 v[108:111], v[174:177], v[198:201], v[108:111]
	v_mfma_f32_16x16x32_bf16 v[108:111], v[178:181], v[202:205], v[108:111]
	v_mfma_f32_16x16x32_bf16 v[104:107], v[182:185], v[198:201], v[104:107]
	v_mfma_f32_16x16x32_bf16 v[104:107], v[186:189], v[202:205], v[104:107]
	v_mfma_f32_16x16x32_bf16 v[120:123], v[182:185], v[190:193], v[120:123]
	v_mfma_f32_16x16x32_bf16 v[120:123], v[186:189], v[194:197], v[120:123]
	v_mfma_f32_16x16x32_bf16 v[124:127], v[174:177], v[190:193], v[124:127]
	v_mfma_f32_16x16x32_bf16 v[124:127], v[178:181], v[194:197], v[124:127]
	s_barrier
	s_add_u32 s12, s52, 0x8000
	s_addc_u32 s13, s53, 0
	s_add_i32 s14, s14, s2
	v_lshl_add_u64 v[224:225], s[12:13], 0, v[134:135]
	s_mov_b32 m0, s14
	ds_read_b128 v[190:193], v155 offset:49152
	ds_read_b128 v[194:197], v155 offset:50176
	ds_read_b128 v[198:201], v155 offset:51200
	ds_read_b128 v[202:205], v155 offset:52224
	ds_read_b128 v[206:209], v155 offset:53248
	ds_read_b128 v[210:213], v155 offset:54272
	ds_read_b128 v[214:217], v155 offset:55296
	ds_read_b128 v[218:221], v155 offset:56320
	global_load_lds_dwordx4 v[224:225], off
	s_add_i32 m0, s14, 0x2000
	v_lshl_add_u64 v[224:225], s[12:13], 0, v[138:139]
	s_add_u32 s12, s52, 0xc000
	s_addc_u32 s13, s53, 0
	s_add_i32 s14, s69, s2
	global_load_lds_dwordx4 v[224:225], off
	v_lshl_add_u64 v[224:225], s[12:13], 0, v[134:135]
	s_mov_b32 m0, s14
	v_lshl_add_u64 v[144:145], v[144:145], 0, s[40:41]
	global_load_lds_dwordx4 v[224:225], off
	v_lshl_add_u64 v[224:225], s[12:13], 0, v[138:139]
	s_add_i32 m0, s14, 0x2000
	s_nop 0
	global_load_lds_dwordx4 v[224:225], off
	s_mov_b32 m0, s33
	s_nop 0
	global_load_lds_dwordx4 v[144:145], off
	v_lshl_add_u64 v[144:145], v[222:223], 0, s[40:41]
	s_mov_b32 m0, s54
	s_nop 0
	global_load_lds_dwordx4 v[144:145], off
	s_waitcnt vmcnt(8)
	s_waitcnt lgkmcnt(0)
	s_barrier
	v_mfma_f32_16x16x32_bf16 v[76:79], v[158:161], v[190:193], v[76:79]
	v_mfma_f32_16x16x32_bf16 v[76:79], v[162:165], v[194:197], v[76:79]
	v_mfma_f32_16x16x32_bf16 v[52:55], v[166:169], v[190:193], v[52:55]
	v_mfma_f32_16x16x32_bf16 v[52:55], v[170:173], v[194:197], v[52:55]
	v_mfma_f32_16x16x32_bf16 v[36:39], v[166:169], v[198:201], v[36:39]
	v_mfma_f32_16x16x32_bf16 v[36:39], v[170:173], v[202:205], v[36:39]
	v_mfma_f32_16x16x32_bf16 v[48:51], v[158:161], v[198:201], v[48:51]
	v_mfma_f32_16x16x32_bf16 v[48:51], v[162:165], v[202:205], v[48:51]
	v_mfma_f32_16x16x32_bf16 v[32:35], v[158:161], v[206:209], v[32:35]
	v_mfma_f32_16x16x32_bf16 v[32:35], v[162:165], v[210:213], v[32:35]
	v_mfma_f32_16x16x32_bf16 v[20:23], v[166:169], v[206:209], v[20:23]
	v_mfma_f32_16x16x32_bf16 v[20:23], v[170:173], v[210:213], v[20:23]
	v_mfma_f32_16x16x32_bf16 v[4:7], v[166:169], v[214:217], v[4:7]
	v_mfma_f32_16x16x32_bf16 v[4:7], v[170:173], v[218:221], v[4:7]
	v_mfma_f32_16x16x32_bf16 v[16:19], v[158:161], v[214:217], v[16:19]
	v_mfma_f32_16x16x32_bf16 v[16:19], v[162:165], v[218:221], v[16:19]
	v_mfma_f32_16x16x32_bf16 v[12:15], v[174:177], v[214:217], v[12:15]
	v_mfma_f32_16x16x32_bf16 v[12:15], v[178:181], v[218:221], v[12:15]
	v_mfma_f32_16x16x32_bf16 v[8:11], v[182:185], v[214:217], v[8:11]
	v_mfma_f32_16x16x32_bf16 v[8:11], v[186:189], v[218:221], v[8:11]
	v_mfma_f32_16x16x32_bf16 v[24:27], v[182:185], v[206:209], v[24:27]
	v_mfma_f32_16x16x32_bf16 v[24:27], v[186:189], v[210:213], v[24:27]
	v_mfma_f32_16x16x32_bf16 v[28:31], v[174:177], v[206:209], v[28:31]
	v_mfma_f32_16x16x32_bf16 v[28:31], v[178:181], v[210:213], v[28:31]
	v_mfma_f32_16x16x32_bf16 v[44:47], v[174:177], v[198:201], v[44:47]
	v_mfma_f32_16x16x32_bf16 v[44:47], v[178:181], v[202:205], v[44:47]
	v_mfma_f32_16x16x32_bf16 v[40:43], v[182:185], v[198:201], v[40:43]
	v_mfma_f32_16x16x32_bf16 v[40:43], v[186:189], v[202:205], v[40:43]
	v_mfma_f32_16x16x32_bf16 v[56:59], v[182:185], v[190:193], v[56:59]
	v_mfma_f32_16x16x32_bf16 v[56:59], v[186:189], v[194:197], v[56:59]
	v_mfma_f32_16x16x32_bf16 v[60:63], v[174:177], v[190:193], v[60:63]
	v_mfma_f32_16x16x32_bf16 v[60:63], v[178:181], v[194:197], v[60:63]
	s_barrier
	s_add_i32 s0, s0, 2
	s_add_u32 s1, s1, 0x10000
	s_addc_u32 s64, s64, 0
	s_add_u32 s65, s65, 0x100
	s_addc_u32 s66, s66, 0
	s_add_u32 s50, s50, 0xffffff00
	s_addc_u32 s51, s51, -1
	v_lshl_add_u64 v[2:3], v[2:3], 0, s[44:45]
	s_cmpk_gt_u32 s0, 0xa9
	v_lshl_add_u64 v[148:149], v[148:149], 0, s[44:45]
	s_cbranch_scc0 .LBB0_762
	s_and_b64 vcc, exec, s[42:43]
	s_cbranch_vccz .LBB0_765
	s_barrier

.LBB0_801:
	ds_read_b128 v[158:161], v155
	ds_read_b128 v[162:165], v155 offset:1024
	ds_read_b128 v[166:169], v155 offset:2048
	ds_read_b128 v[170:173], v155 offset:3072
	ds_read_b128 v[174:177], v156
	ds_read_b128 v[178:181], v156 offset:1024
	ds_read_b128 v[182:185], v156 offset:2048
	ds_read_b128 v[186:189], v156 offset:3072
	s_add_u32 s12, s72, s36
	s_addc_u32 s13, s73, 0
	s_cmp_eq_u32 s36, s8
	s_cselect_b32 s23, s0, s13
	s_cselect_b32 s22, s1, s12
	s_cselect_b32 s57, s45, s71
	s_cselect_b32 s56, s68, s70
	s_add_i32 s75, s33, 0xc000
	v_lshl_add_u64 v[144:145], v[2:3], 0, s[36:37]
	s_mov_b32 m0, s75
	s_add_i32 s74, s33, 0xe000
	ds_read_b128 v[190:193], v157
	ds_read_b128 v[194:197], v157 offset:1024
	ds_read_b128 v[198:201], v157 offset:2048
	ds_read_b128 v[202:205], v157 offset:3072
	ds_read_b128 v[206:209], v157 offset:4096
	ds_read_b128 v[210:213], v157 offset:5120
	ds_read_b128 v[214:217], v157 offset:6144
	ds_read_b128 v[218:221], v157 offset:7168
	global_load_lds_dwordx4 v[144:145], off
	v_lshl_add_u64 v[144:145], v[148:149], 0, s[36:37]
	s_mov_b32 m0, s74
	s_nop 0
	global_load_lds_dwordx4 v[144:145], off
	s_waitcnt vmcnt(8)
	s_waitcnt lgkmcnt(0)
	s_barrier
	v_mfma_f32_16x16x32_bf16 v[120:123], v[158:161], v[190:193], v[120:123]
	v_mfma_f32_16x16x32_bf16 v[120:123], v[162:165], v[194:197], v[120:123]
	v_mfma_f32_16x16x32_bf16 v[116:119], v[166:169], v[190:193], v[116:119]
	v_mfma_f32_16x16x32_bf16 v[116:119], v[170:173], v[194:197], v[116:119]
	v_mfma_f32_16x16x32_bf16 v[100:103], v[166:169], v[198:201], v[100:103]
	v_mfma_f32_16x16x32_bf16 v[100:103], v[170:173], v[202:205], v[100:103]
	v_mfma_f32_16x16x32_bf16 v[104:107], v[158:161], v[198:201], v[104:107]
	v_mfma_f32_16x16x32_bf16 v[104:107], v[162:165], v[202:205], v[104:107]
	v_mfma_f32_16x16x32_bf16 v[88:91], v[158:161], v[206:209], v[88:91]
	v_mfma_f32_16x16x32_bf16 v[88:91], v[162:165], v[210:213], v[88:91]
	v_mfma_f32_16x16x32_bf16 v[84:87], v[166:169], v[206:209], v[84:87]
	v_mfma_f32_16x16x32_bf16 v[84:87], v[170:173], v[210:213], v[84:87]
	v_mfma_f32_16x16x32_bf16 v[68:71], v[166:169], v[214:217], v[68:71]
	v_mfma_f32_16x16x32_bf16 v[68:71], v[170:173], v[218:221], v[68:71]
	v_mfma_f32_16x16x32_bf16 v[72:75], v[158:161], v[214:217], v[72:75]
	v_mfma_f32_16x16x32_bf16 v[72:75], v[162:165], v[218:221], v[72:75]
	v_mfma_f32_16x16x32_bf16 v[80:83], v[174:177], v[214:217], v[80:83]
	v_mfma_f32_16x16x32_bf16 v[80:83], v[178:181], v[218:221], v[80:83]
	v_mfma_f32_16x16x32_bf16 v[76:79], v[182:185], v[214:217], v[76:79]
	v_mfma_f32_16x16x32_bf16 v[76:79], v[186:189], v[218:221], v[76:79]
	v_mfma_f32_16x16x32_bf16 v[92:95], v[182:185], v[206:209], v[92:95]
	v_mfma_f32_16x16x32_bf16 v[92:95], v[186:189], v[210:213], v[92:95]
	v_mfma_f32_16x16x32_bf16 v[96:99], v[174:177], v[206:209], v[96:99]
	v_mfma_f32_16x16x32_bf16 v[96:99], v[178:181], v[210:213], v[96:99]
	v_mfma_f32_16x16x32_bf16 v[112:115], v[174:177], v[198:201], v[112:115]
	v_mfma_f32_16x16x32_bf16 v[112:115], v[178:181], v[202:205], v[112:115]
	v_mfma_f32_16x16x32_bf16 v[108:111], v[182:185], v[198:201], v[108:111]
	v_mfma_f32_16x16x32_bf16 v[108:111], v[186:189], v[202:205], v[108:111]
	v_mfma_f32_16x16x32_bf16 v[124:127], v[182:185], v[190:193], v[124:127]
	v_mfma_f32_16x16x32_bf16 v[124:127], v[186:189], v[194:197], v[124:127]
	v_mfma_f32_16x16x32_bf16 v[128:131], v[174:177], v[190:193], v[128:131]
	v_mfma_f32_16x16x32_bf16 v[128:131], v[178:181], v[194:197], v[128:131]
	s_barrier
	s_add_i32 s12, s60, s2
	v_lshl_add_u64 v[144:145], s[56:57], 0, v[134:135]
	s_mov_b32 m0, s12
	ds_read_b128 v[190:193], v157 offset:16384
	ds_read_b128 v[194:197], v157 offset:17408
	ds_read_b128 v[198:201], v157 offset:18432
	ds_read_b128 v[202:205], v157 offset:19456
	ds_read_b128 v[206:209], v157 offset:20480
	ds_read_b128 v[210:213], v157 offset:21504
	ds_read_b128 v[214:217], v157 offset:22528
	ds_read_b128 v[218:221], v157 offset:23552
	global_load_lds_dwordx4 v[144:145], off
	s_add_i32 m0, s12, 0x2000
	s_add_u32 s12, s56, 0x4000
	v_lshl_add_u64 v[144:145], s[56:57], 0, v[138:139]
	s_addc_u32 s13, s57, 0
	s_add_i32 s14, s61, s2
	global_load_lds_dwordx4 v[144:145], off
	v_lshl_add_u64 v[144:145], s[12:13], 0, v[134:135]
	s_mov_b32 m0, s14
	v_lshl_add_u64 v[222:223], s[22:23], 0, v[136:137]
	global_load_lds_dwordx4 v[144:145], off
	v_lshl_add_u64 v[144:145], s[12:13], 0, v[138:139]
	s_add_i32 m0, s14, 0x2000
	s_nop 0
	global_load_lds_dwordx4 v[144:145], off
	v_lshl_add_u64 v[144:145], s[22:23], 0, v[132:133]
	s_mov_b32 m0, s33
	s_nop 0
	global_load_lds_dwordx4 v[144:145], off
	s_mov_b32 m0, s53
	s_nop 0
	global_load_lds_dwordx4 v[222:223], off
	s_waitcnt vmcnt(8)
	s_waitcnt lgkmcnt(0)
	s_barrier
	v_mfma_f32_16x16x32_bf16 v[56:59], v[158:161], v[190:193], v[56:59]
	v_mfma_f32_16x16x32_bf16 v[56:59], v[162:165], v[194:197], v[56:59]
	v_mfma_f32_16x16x32_bf16 v[52:55], v[166:169], v[190:193], v[52:55]
	v_mfma_f32_16x16x32_bf16 v[52:55], v[170:173], v[194:197], v[52:55]
	v_mfma_f32_16x16x32_bf16 v[36:39], v[166:169], v[198:201], v[36:39]
	v_mfma_f32_16x16x32_bf16 v[36:39], v[170:173], v[202:205], v[36:39]
	v_mfma_f32_16x16x32_bf16 v[40:43], v[158:161], v[198:201], v[40:43]
	v_mfma_f32_16x16x32_bf16 v[40:43], v[162:165], v[202:205], v[40:43]
	v_mfma_f32_16x16x32_bf16 v[24:27], v[158:161], v[206:209], v[24:27]
	v_mfma_f32_16x16x32_bf16 v[24:27], v[162:165], v[210:213], v[24:27]
	v_mfma_f32_16x16x32_bf16 v[20:23], v[166:169], v[206:209], v[20:23]
	v_mfma_f32_16x16x32_bf16 v[20:23], v[170:173], v[210:213], v[20:23]
	v_mfma_f32_16x16x32_bf16 v[4:7], v[166:169], v[214:217], v[4:7]
	v_mfma_f32_16x16x32_bf16 v[4:7], v[170:173], v[218:221], v[4:7]
	v_mfma_f32_16x16x32_bf16 v[8:11], v[158:161], v[214:217], v[8:11]
	v_mfma_f32_16x16x32_bf16 v[8:11], v[162:165], v[218:221], v[8:11]
	v_mfma_f32_16x16x32_bf16 v[16:19], v[174:177], v[214:217], v[16:19]
	v_mfma_f32_16x16x32_bf16 v[16:19], v[178:181], v[218:221], v[16:19]
	v_mfma_f32_16x16x32_bf16 v[12:15], v[182:185], v[214:217], v[12:15]
	v_mfma_f32_16x16x32_bf16 v[12:15], v[186:189], v[218:221], v[12:15]
	v_mfma_f32_16x16x32_bf16 v[28:31], v[182:185], v[206:209], v[28:31]
	v_mfma_f32_16x16x32_bf16 v[28:31], v[186:189], v[210:213], v[28:31]
	v_mfma_f32_16x16x32_bf16 v[32:35], v[174:177], v[206:209], v[32:35]
	v_mfma_f32_16x16x32_bf16 v[32:35], v[178:181], v[210:213], v[32:35]
	v_mfma_f32_16x16x32_bf16 v[48:51], v[174:177], v[198:201], v[48:51]
	v_mfma_f32_16x16x32_bf16 v[48:51], v[178:181], v[202:205], v[48:51]
	v_mfma_f32_16x16x32_bf16 v[44:47], v[182:185], v[198:201], v[44:47]
	v_mfma_f32_16x16x32_bf16 v[44:47], v[186:189], v[202:205], v[44:47]
	v_mfma_f32_16x16x32_bf16 v[60:63], v[182:185], v[190:193], v[60:63]
	v_mfma_f32_16x16x32_bf16 v[60:63], v[186:189], v[194:197], v[60:63]
	v_mfma_f32_16x16x32_bf16 v[64:67], v[174:177], v[190:193], v[64:67]
	v_mfma_f32_16x16x32_bf16 v[64:67], v[178:181], v[194:197], v[64:67]
	s_barrier
	s_add_i32 s14, 0, 0x18000
	v_add_u32_e32 v1, s14, v152
	s_add_i32 s76, 0, 0x1c000
	ds_read_b128 v[158:161], v1
	ds_read_b128 v[162:165], v1 offset:1024
	ds_read_b128 v[166:169], v1 offset:2048
	ds_read_b128 v[170:173], v1 offset:3072
	v_add_u32_e32 v1, s76, v152
	ds_read_b128 v[174:177], v1
	ds_read_b128 v[178:181], v1 offset:1024
	ds_read_b128 v[182:185], v1 offset:2048
	ds_read_b128 v[186:189], v1 offset:3072
	s_add_u32 s12, s22, 0x100000
	s_addc_u32 s13, s23, 0
	s_mov_b32 m0, s55
	v_lshl_add_u64 v[224:225], s[12:13], 0, v[132:133]
	ds_read_b128 v[190:193], v157 offset:32768
	ds_read_b128 v[194:197], v157 offset:33792
	ds_read_b128 v[198:201], v157 offset:34816
	ds_read_b128 v[202:205], v157 offset:35840
	ds_read_b128 v[206:209], v157 offset:36864
	ds_read_b128 v[210:213], v157 offset:37888
	ds_read_b128 v[214:217], v157 offset:38912
	ds_read_b128 v[218:221], v157 offset:39936
	global_load_lds_dwordx4 v[224:225], off
	v_lshl_add_u64 v[224:225], s[12:13], 0, v[136:137]
	s_mov_b32 m0, s58
	s_nop 0
	global_load_lds_dwordx4 v[224:225], off
	s_waitcnt vmcnt(8)
	s_waitcnt lgkmcnt(0)
	s_barrier
	v_mfma_f32_16x16x32_bf16 v[120:123], v[158:161], v[190:193], v[120:123]
	v_mfma_f32_16x16x32_bf16 v[120:123], v[162:165], v[194:197], v[120:123]
	v_mfma_f32_16x16x32_bf16 v[116:119], v[166:169], v[190:193], v[116:119]
	v_mfma_f32_16x16x32_bf16 v[116:119], v[170:173], v[194:197], v[116:119]
	v_mfma_f32_16x16x32_bf16 v[100:103], v[166:169], v[198:201], v[100:103]
	v_mfma_f32_16x16x32_bf16 v[100:103], v[170:173], v[202:205], v[100:103]
	v_mfma_f32_16x16x32_bf16 v[104:107], v[158:161], v[198:201], v[104:107]
	v_mfma_f32_16x16x32_bf16 v[104:107], v[162:165], v[202:205], v[104:107]
	v_mfma_f32_16x16x32_bf16 v[88:91], v[158:161], v[206:209], v[88:91]
	v_mfma_f32_16x16x32_bf16 v[88:91], v[162:165], v[210:213], v[88:91]
	v_mfma_f32_16x16x32_bf16 v[84:87], v[166:169], v[206:209], v[84:87]
	v_mfma_f32_16x16x32_bf16 v[84:87], v[170:173], v[210:213], v[84:87]
	v_mfma_f32_16x16x32_bf16 v[68:71], v[166:169], v[214:217], v[68:71]
	v_mfma_f32_16x16x32_bf16 v[68:71], v[170:173], v[218:221], v[68:71]
	v_mfma_f32_16x16x32_bf16 v[72:75], v[158:161], v[214:217], v[72:75]
	v_mfma_f32_16x16x32_bf16 v[72:75], v[162:165], v[218:221], v[72:75]
	v_mfma_f32_16x16x32_bf16 v[80:83], v[174:177], v[214:217], v[80:83]
	v_mfma_f32_16x16x32_bf16 v[80:83], v[178:181], v[218:221], v[80:83]
	v_mfma_f32_16x16x32_bf16 v[76:79], v[182:185], v[214:217], v[76:79]
	v_mfma_f32_16x16x32_bf16 v[76:79], v[186:189], v[218:221], v[76:79]
	v_mfma_f32_16x16x32_bf16 v[92:95], v[182:185], v[206:209], v[92:95]
	v_mfma_f32_16x16x32_bf16 v[92:95], v[186:189], v[210:213], v[92:95]
	v_mfma_f32_16x16x32_bf16 v[96:99], v[174:177], v[206:209], v[96:99]
	v_mfma_f32_16x16x32_bf16 v[96:99], v[178:181], v[210:213], v[96:99]
	v_mfma_f32_16x16x32_bf16 v[112:115], v[174:177], v[198:201], v[112:115]
	v_mfma_f32_16x16x32_bf16 v[112:115], v[178:181], v[202:205], v[112:115]
	v_mfma_f32_16x16x32_bf16 v[108:111], v[182:185], v[198:201], v[108:111]
	v_mfma_f32_16x16x32_bf16 v[108:111], v[186:189], v[202:205], v[108:111]
	v_mfma_f32_16x16x32_bf16 v[124:127], v[182:185], v[190:193], v[124:127]
	v_mfma_f32_16x16x32_bf16 v[124:127], v[186:189], v[194:197], v[124:127]
	v_mfma_f32_16x16x32_bf16 v[128:131], v[174:177], v[190:193], v[128:131]
	v_mfma_f32_16x16x32_bf16 v[128:131], v[178:181], v[194:197], v[128:131]
	s_barrier
	s_add_u32 s12, s56, 0x8000
	s_addc_u32 s13, s57, 0
	s_add_i32 s14, s14, s2
	v_lshl_add_u64 v[224:225], s[12:13], 0, v[134:135]
	s_mov_b32 m0, s14
	ds_read_b128 v[190:193], v157 offset:49152
	ds_read_b128 v[194:197], v157 offset:50176
	ds_read_b128 v[198:201], v157 offset:51200
	ds_read_b128 v[202:205], v157 offset:52224
	ds_read_b128 v[206:209], v157 offset:53248
	ds_read_b128 v[210:213], v157 offset:54272
	ds_read_b128 v[214:217], v157 offset:55296
	ds_read_b128 v[218:221], v157 offset:56320
	global_load_lds_dwordx4 v[224:225], off
	s_add_i32 m0, s14, 0x2000
	v_lshl_add_u64 v[224:225], s[12:13], 0, v[138:139]
	s_add_u32 s12, s56, 0xc000
	s_addc_u32 s13, s57, 0
	s_add_i32 s14, s76, s2
	global_load_lds_dwordx4 v[224:225], off
	v_lshl_add_u64 v[224:225], s[12:13], 0, v[134:135]
	s_mov_b32 m0, s14
	v_lshl_add_u64 v[144:145], v[144:145], 0, s[34:35]
	global_load_lds_dwordx4 v[224:225], off
	v_lshl_add_u64 v[224:225], s[12:13], 0, v[138:139]
	s_add_i32 m0, s14, 0x2000
	s_nop 0
	global_load_lds_dwordx4 v[224:225], off
	s_mov_b32 m0, s16
	s_nop 0
	global_load_lds_dwordx4 v[144:145], off
	v_lshl_add_u64 v[144:145], v[222:223], 0, s[34:35]
	s_mov_b32 m0, s59
	s_nop 0
	global_load_lds_dwordx4 v[144:145], off
	s_waitcnt vmcnt(8)
	s_waitcnt lgkmcnt(0)
	s_barrier
	v_mfma_f32_16x16x32_bf16 v[56:59], v[158:161], v[190:193], v[56:59]
	v_mfma_f32_16x16x32_bf16 v[56:59], v[162:165], v[194:197], v[56:59]
	v_mfma_f32_16x16x32_bf16 v[52:55], v[166:169], v[190:193], v[52:55]
	v_mfma_f32_16x16x32_bf16 v[52:55], v[170:173], v[194:197], v[52:55]
	v_mfma_f32_16x16x32_bf16 v[36:39], v[166:169], v[198:201], v[36:39]
	v_mfma_f32_16x16x32_bf16 v[36:39], v[170:173], v[202:205], v[36:39]
	v_mfma_f32_16x16x32_bf16 v[40:43], v[158:161], v[198:201], v[40:43]
	v_mfma_f32_16x16x32_bf16 v[40:43], v[162:165], v[202:205], v[40:43]
	v_mfma_f32_16x16x32_bf16 v[24:27], v[158:161], v[206:209], v[24:27]
	v_mfma_f32_16x16x32_bf16 v[24:27], v[162:165], v[210:213], v[24:27]
	v_mfma_f32_16x16x32_bf16 v[20:23], v[166:169], v[206:209], v[20:23]
	v_mfma_f32_16x16x32_bf16 v[20:23], v[170:173], v[210:213], v[20:23]
	v_mfma_f32_16x16x32_bf16 v[4:7], v[166:169], v[214:217], v[4:7]
	v_mfma_f32_16x16x32_bf16 v[4:7], v[170:173], v[218:221], v[4:7]
	v_mfma_f32_16x16x32_bf16 v[8:11], v[158:161], v[214:217], v[8:11]
	v_mfma_f32_16x16x32_bf16 v[8:11], v[162:165], v[218:221], v[8:11]
	v_mfma_f32_16x16x32_bf16 v[16:19], v[174:177], v[214:217], v[16:19]
	v_mfma_f32_16x16x32_bf16 v[16:19], v[178:181], v[218:221], v[16:19]
	v_mfma_f32_16x16x32_bf16 v[12:15], v[182:185], v[214:217], v[12:15]
	v_mfma_f32_16x16x32_bf16 v[12:15], v[186:189], v[218:221], v[12:15]
	v_mfma_f32_16x16x32_bf16 v[28:31], v[182:185], v[206:209], v[28:31]
	v_mfma_f32_16x16x32_bf16 v[28:31], v[186:189], v[210:213], v[28:31]
	v_mfma_f32_16x16x32_bf16 v[32:35], v[174:177], v[206:209], v[32:35]
	v_mfma_f32_16x16x32_bf16 v[32:35], v[178:181], v[210:213], v[32:35]
	v_mfma_f32_16x16x32_bf16 v[48:51], v[174:177], v[198:201], v[48:51]
	v_mfma_f32_16x16x32_bf16 v[48:51], v[178:181], v[202:205], v[48:51]
	v_mfma_f32_16x16x32_bf16 v[44:47], v[182:185], v[198:201], v[44:47]
	v_mfma_f32_16x16x32_bf16 v[44:47], v[186:189], v[202:205], v[44:47]
	v_mfma_f32_16x16x32_bf16 v[60:63], v[182:185], v[190:193], v[60:63]
	v_mfma_f32_16x16x32_bf16 v[60:63], v[186:189], v[194:197], v[60:63]
	v_mfma_f32_16x16x32_bf16 v[64:67], v[174:177], v[190:193], v[64:67]
	v_mfma_f32_16x16x32_bf16 v[64:67], v[178:181], v[194:197], v[64:67]
	s_barrier
	s_add_i32 s69, s69, 2
	s_add_u32 s70, s70, 0x10000
	s_addc_u32 s71, s71, 0
	s_add_u32 s72, s72, 0x100
	s_addc_u32 s73, s73, 0
	s_add_u32 s8, s8, 0xffffff00
	s_addc_u32 s9, s9, -1
	v_lshl_add_u64 v[2:3], v[2:3], 0, s[40:41]
	s_cmp_gt_u32 s69, 61
	v_lshl_add_u64 v[148:149], v[148:149], 0, s[40:41]
	s_cbranch_scc0 .LBB0_801
	s_and_b64 vcc, exec, s[38:39]
	s_cbranch_vccnz .LBB0_809
	s_and_b64 s[0:1], s[10:11], s[6:7]
	s_andn2_b64 vcc, exec, s[0:1]
	s_cbranch_vccz .LBB0_810

.LBB0_896:
	ds_read_b128 v[158:161], v153
	ds_read_b128 v[162:165], v153 offset:1024
	ds_read_b128 v[166:169], v153 offset:2048
	ds_read_b128 v[170:173], v153 offset:3072
	ds_read_b128 v[174:177], v154
	ds_read_b128 v[178:181], v154 offset:1024
	ds_read_b128 v[182:185], v154 offset:2048
	ds_read_b128 v[186:189], v154 offset:3072
	s_add_u32 s12, s60, s26
	s_addc_u32 s13, s61, 0
	s_cmp_eq_u32 s26, s46
	s_cselect_b32 s23, s9, s13
	s_cselect_b32 s22, s8, s12
	s_cselect_b32 s49, s45, s59
	s_cselect_b32 s48, s44, s1
	s_add_i32 s63, s18, 0xc000
	v_lshl_add_u64 v[144:145], v[2:3], 0, s[26:27]
	s_mov_b32 m0, s63
	s_add_i32 s62, s18, 0xe000
	ds_read_b128 v[190:193], v155
	ds_read_b128 v[194:197], v155 offset:1024
	ds_read_b128 v[198:201], v155 offset:2048
	ds_read_b128 v[202:205], v155 offset:3072
	ds_read_b128 v[206:209], v155 offset:4096
	ds_read_b128 v[210:213], v155 offset:5120
	ds_read_b128 v[214:217], v155 offset:6144
	ds_read_b128 v[218:221], v155 offset:7168
	global_load_lds_dwordx4 v[144:145], off
	v_lshl_add_u64 v[144:145], v[148:149], 0, s[26:27]
	s_mov_b32 m0, s62
	s_nop 0
	global_load_lds_dwordx4 v[144:145], off
	s_waitcnt vmcnt(8)
	s_waitcnt lgkmcnt(0)
	s_barrier
	v_mfma_f32_16x16x32_bf16 v[128:131], v[158:161], v[190:193], v[128:131]
	v_mfma_f32_16x16x32_bf16 v[128:131], v[162:165], v[194:197], v[128:131]
	v_mfma_f32_16x16x32_bf16 v[116:119], v[166:169], v[190:193], v[116:119]
	v_mfma_f32_16x16x32_bf16 v[116:119], v[170:173], v[194:197], v[116:119]
	v_mfma_f32_16x16x32_bf16 v[100:103], v[166:169], v[198:201], v[100:103]
	v_mfma_f32_16x16x32_bf16 v[100:103], v[170:173], v[202:205], v[100:103]
	v_mfma_f32_16x16x32_bf16 v[112:115], v[158:161], v[198:201], v[112:115]
	v_mfma_f32_16x16x32_bf16 v[112:115], v[162:165], v[202:205], v[112:115]
	v_mfma_f32_16x16x32_bf16 v[96:99], v[158:161], v[206:209], v[96:99]
	v_mfma_f32_16x16x32_bf16 v[96:99], v[162:165], v[210:213], v[96:99]
	v_mfma_f32_16x16x32_bf16 v[84:87], v[166:169], v[206:209], v[84:87]
	v_mfma_f32_16x16x32_bf16 v[84:87], v[170:173], v[210:213], v[84:87]
	v_mfma_f32_16x16x32_bf16 v[64:67], v[166:169], v[214:217], v[64:67]
	v_mfma_f32_16x16x32_bf16 v[64:67], v[170:173], v[218:221], v[64:67]
	v_mfma_f32_16x16x32_bf16 v[80:83], v[158:161], v[214:217], v[80:83]
	v_mfma_f32_16x16x32_bf16 v[80:83], v[162:165], v[218:221], v[80:83]
	v_mfma_f32_16x16x32_bf16 v[72:75], v[174:177], v[214:217], v[72:75]
	v_mfma_f32_16x16x32_bf16 v[72:75], v[178:181], v[218:221], v[72:75]
	v_mfma_f32_16x16x32_bf16 v[68:71], v[182:185], v[214:217], v[68:71]
	v_mfma_f32_16x16x32_bf16 v[68:71], v[186:189], v[218:221], v[68:71]
	v_mfma_f32_16x16x32_bf16 v[88:91], v[182:185], v[206:209], v[88:91]
	v_mfma_f32_16x16x32_bf16 v[88:91], v[186:189], v[210:213], v[88:91]
	v_mfma_f32_16x16x32_bf16 v[92:95], v[174:177], v[206:209], v[92:95]
	v_mfma_f32_16x16x32_bf16 v[92:95], v[178:181], v[210:213], v[92:95]
	v_mfma_f32_16x16x32_bf16 v[108:111], v[174:177], v[198:201], v[108:111]
	v_mfma_f32_16x16x32_bf16 v[108:111], v[178:181], v[202:205], v[108:111]
	v_mfma_f32_16x16x32_bf16 v[104:107], v[182:185], v[198:201], v[104:107]
	v_mfma_f32_16x16x32_bf16 v[104:107], v[186:189], v[202:205], v[104:107]
	v_mfma_f32_16x16x32_bf16 v[120:123], v[182:185], v[190:193], v[120:123]
	v_mfma_f32_16x16x32_bf16 v[120:123], v[186:189], v[194:197], v[120:123]
	v_mfma_f32_16x16x32_bf16 v[124:127], v[174:177], v[190:193], v[124:127]
	v_mfma_f32_16x16x32_bf16 v[124:127], v[178:181], v[194:197], v[124:127]
	s_barrier
	s_add_i32 s12, s52, s17
	v_lshl_add_u64 v[144:145], s[48:49], 0, v[134:135]
	s_mov_b32 m0, s12
	ds_read_b128 v[190:193], v155 offset:16384
	ds_read_b128 v[194:197], v155 offset:17408
	ds_read_b128 v[198:201], v155 offset:18432
	ds_read_b128 v[202:205], v155 offset:19456
	ds_read_b128 v[206:209], v155 offset:20480
	ds_read_b128 v[210:213], v155 offset:21504
	ds_read_b128 v[214:217], v155 offset:22528
	ds_read_b128 v[218:221], v155 offset:23552
	global_load_lds_dwordx4 v[144:145], off
	s_add_i32 m0, s12, 0x2000
	s_add_u32 s12, s48, 0x4000
	v_lshl_add_u64 v[144:145], s[48:49], 0, v[138:139]
	s_addc_u32 s13, s49, 0
	s_add_i32 s14, s53, s17
	global_load_lds_dwordx4 v[144:145], off
	v_lshl_add_u64 v[144:145], s[12:13], 0, v[134:135]
	s_mov_b32 m0, s14
	v_lshl_add_u64 v[222:223], s[22:23], 0, v[136:137]
	global_load_lds_dwordx4 v[144:145], off
	v_lshl_add_u64 v[144:145], s[12:13], 0, v[138:139]
	s_add_i32 m0, s14, 0x2000
	s_nop 0
	global_load_lds_dwordx4 v[144:145], off
	v_lshl_add_u64 v[144:145], s[22:23], 0, v[132:133]
	s_mov_b32 m0, s18
	s_nop 0
	global_load_lds_dwordx4 v[144:145], off
	s_mov_b32 m0, s19
	s_nop 0
	global_load_lds_dwordx4 v[222:223], off
	s_waitcnt vmcnt(8)
	s_waitcnt lgkmcnt(0)
	s_barrier
	v_mfma_f32_16x16x32_bf16 v[76:79], v[158:161], v[190:193], v[76:79]
	v_mfma_f32_16x16x32_bf16 v[76:79], v[162:165], v[194:197], v[76:79]
	v_mfma_f32_16x16x32_bf16 v[52:55], v[166:169], v[190:193], v[52:55]
	v_mfma_f32_16x16x32_bf16 v[52:55], v[170:173], v[194:197], v[52:55]
	v_mfma_f32_16x16x32_bf16 v[36:39], v[166:169], v[198:201], v[36:39]
	v_mfma_f32_16x16x32_bf16 v[36:39], v[170:173], v[202:205], v[36:39]
	v_mfma_f32_16x16x32_bf16 v[48:51], v[158:161], v[198:201], v[48:51]
	v_mfma_f32_16x16x32_bf16 v[48:51], v[162:165], v[202:205], v[48:51]
	v_mfma_f32_16x16x32_bf16 v[32:35], v[158:161], v[206:209], v[32:35]
	v_mfma_f32_16x16x32_bf16 v[32:35], v[162:165], v[210:213], v[32:35]
	v_mfma_f32_16x16x32_bf16 v[20:23], v[166:169], v[206:209], v[20:23]
	v_mfma_f32_16x16x32_bf16 v[20:23], v[170:173], v[210:213], v[20:23]
	v_mfma_f32_16x16x32_bf16 v[4:7], v[166:169], v[214:217], v[4:7]
	v_mfma_f32_16x16x32_bf16 v[4:7], v[170:173], v[218:221], v[4:7]
	v_mfma_f32_16x16x32_bf16 v[16:19], v[158:161], v[214:217], v[16:19]
	v_mfma_f32_16x16x32_bf16 v[16:19], v[162:165], v[218:221], v[16:19]
	v_mfma_f32_16x16x32_bf16 v[12:15], v[174:177], v[214:217], v[12:15]
	v_mfma_f32_16x16x32_bf16 v[12:15], v[178:181], v[218:221], v[12:15]
	v_mfma_f32_16x16x32_bf16 v[8:11], v[182:185], v[214:217], v[8:11]
	v_mfma_f32_16x16x32_bf16 v[8:11], v[186:189], v[218:221], v[8:11]
	v_mfma_f32_16x16x32_bf16 v[24:27], v[182:185], v[206:209], v[24:27]
	v_mfma_f32_16x16x32_bf16 v[24:27], v[186:189], v[210:213], v[24:27]
	v_mfma_f32_16x16x32_bf16 v[28:31], v[174:177], v[206:209], v[28:31]
	v_mfma_f32_16x16x32_bf16 v[28:31], v[178:181], v[210:213], v[28:31]
	v_mfma_f32_16x16x32_bf16 v[44:47], v[174:177], v[198:201], v[44:47]
	v_mfma_f32_16x16x32_bf16 v[44:47], v[178:181], v[202:205], v[44:47]
	v_mfma_f32_16x16x32_bf16 v[40:43], v[182:185], v[198:201], v[40:43]
	v_mfma_f32_16x16x32_bf16 v[40:43], v[186:189], v[202:205], v[40:43]
	v_mfma_f32_16x16x32_bf16 v[56:59], v[182:185], v[190:193], v[56:59]
	v_mfma_f32_16x16x32_bf16 v[56:59], v[186:189], v[194:197], v[56:59]
	v_mfma_f32_16x16x32_bf16 v[60:63], v[174:177], v[190:193], v[60:63]
	v_mfma_f32_16x16x32_bf16 v[60:63], v[178:181], v[194:197], v[60:63]
	s_barrier
	s_add_i32 s14, 0, 0x18000
	v_add_u32_e32 v1, s14, v151
	s_add_i32 s64, 0, 0x1c000
	ds_read_b128 v[158:161], v1
	ds_read_b128 v[162:165], v1 offset:1024
	ds_read_b128 v[166:169], v1 offset:2048
	ds_read_b128 v[170:173], v1 offset:3072
	v_add_u32_e32 v1, s64, v151
	ds_read_b128 v[174:177], v1
	ds_read_b128 v[178:181], v1 offset:1024
	ds_read_b128 v[182:185], v1 offset:2048
	ds_read_b128 v[186:189], v1 offset:3072
	s_add_u32 s12, s22, 0x2b0000
	s_addc_u32 s13, s23, 0
	s_mov_b32 m0, s20
	v_lshl_add_u64 v[224:225], s[12:13], 0, v[132:133]
	ds_read_b128 v[190:193], v155 offset:32768
	ds_read_b128 v[194:197], v155 offset:33792
	ds_read_b128 v[198:201], v155 offset:34816
	ds_read_b128 v[202:205], v155 offset:35840
	ds_read_b128 v[206:209], v155 offset:36864
	ds_read_b128 v[210:213], v155 offset:37888
	ds_read_b128 v[214:217], v155 offset:38912
	ds_read_b128 v[218:221], v155 offset:39936
	global_load_lds_dwordx4 v[224:225], off
	v_lshl_add_u64 v[224:225], s[12:13], 0, v[136:137]
	s_mov_b32 m0, s21
	s_nop 0
	global_load_lds_dwordx4 v[224:225], off
	s_waitcnt vmcnt(8)
	s_waitcnt lgkmcnt(0)
	s_barrier
	v_mfma_f32_16x16x32_bf16 v[128:131], v[158:161], v[190:193], v[128:131]
	v_mfma_f32_16x16x32_bf16 v[128:131], v[162:165], v[194:197], v[128:131]
	v_mfma_f32_16x16x32_bf16 v[116:119], v[166:169], v[190:193], v[116:119]
	v_mfma_f32_16x16x32_bf16 v[116:119], v[170:173], v[194:197], v[116:119]
	v_mfma_f32_16x16x32_bf16 v[100:103], v[166:169], v[198:201], v[100:103]
	v_mfma_f32_16x16x32_bf16 v[100:103], v[170:173], v[202:205], v[100:103]
	v_mfma_f32_16x16x32_bf16 v[112:115], v[158:161], v[198:201], v[112:115]
	v_mfma_f32_16x16x32_bf16 v[112:115], v[162:165], v[202:205], v[112:115]
	v_mfma_f32_16x16x32_bf16 v[96:99], v[158:161], v[206:209], v[96:99]
	v_mfma_f32_16x16x32_bf16 v[96:99], v[162:165], v[210:213], v[96:99]
	v_mfma_f32_16x16x32_bf16 v[84:87], v[166:169], v[206:209], v[84:87]
	v_mfma_f32_16x16x32_bf16 v[84:87], v[170:173], v[210:213], v[84:87]
	v_mfma_f32_16x16x32_bf16 v[64:67], v[166:169], v[214:217], v[64:67]
	v_mfma_f32_16x16x32_bf16 v[64:67], v[170:173], v[218:221], v[64:67]
	v_mfma_f32_16x16x32_bf16 v[80:83], v[158:161], v[214:217], v[80:83]
	v_mfma_f32_16x16x32_bf16 v[80:83], v[162:165], v[218:221], v[80:83]
	v_mfma_f32_16x16x32_bf16 v[72:75], v[174:177], v[214:217], v[72:75]
	v_mfma_f32_16x16x32_bf16 v[72:75], v[178:181], v[218:221], v[72:75]
	v_mfma_f32_16x16x32_bf16 v[68:71], v[182:185], v[214:217], v[68:71]
	v_mfma_f32_16x16x32_bf16 v[68:71], v[186:189], v[218:221], v[68:71]
	v_mfma_f32_16x16x32_bf16 v[88:91], v[182:185], v[206:209], v[88:91]
	v_mfma_f32_16x16x32_bf16 v[88:91], v[186:189], v[210:213], v[88:91]
	v_mfma_f32_16x16x32_bf16 v[92:95], v[174:177], v[206:209], v[92:95]
	v_mfma_f32_16x16x32_bf16 v[92:95], v[178:181], v[210:213], v[92:95]
	v_mfma_f32_16x16x32_bf16 v[108:111], v[174:177], v[198:201], v[108:111]
	v_mfma_f32_16x16x32_bf16 v[108:111], v[178:181], v[202:205], v[108:111]
	v_mfma_f32_16x16x32_bf16 v[104:107], v[182:185], v[198:201], v[104:107]
	v_mfma_f32_16x16x32_bf16 v[104:107], v[186:189], v[202:205], v[104:107]
	v_mfma_f32_16x16x32_bf16 v[120:123], v[182:185], v[190:193], v[120:123]
	v_mfma_f32_16x16x32_bf16 v[120:123], v[186:189], v[194:197], v[120:123]
	v_mfma_f32_16x16x32_bf16 v[124:127], v[174:177], v[190:193], v[124:127]
	v_mfma_f32_16x16x32_bf16 v[124:127], v[178:181], v[194:197], v[124:127]
	s_barrier
	s_add_u32 s12, s48, 0x8000
	s_addc_u32 s13, s49, 0
	s_add_i32 s14, s14, s17
	v_lshl_add_u64 v[224:225], s[12:13], 0, v[134:135]
	s_mov_b32 m0, s14
	ds_read_b128 v[190:193], v155 offset:49152
	ds_read_b128 v[194:197], v155 offset:50176
	ds_read_b128 v[198:201], v155 offset:51200
	ds_read_b128 v[202:205], v155 offset:52224
	ds_read_b128 v[206:209], v155 offset:53248
	ds_read_b128 v[210:213], v155 offset:54272
	ds_read_b128 v[214:217], v155 offset:55296
	ds_read_b128 v[218:221], v155 offset:56320
	global_load_lds_dwordx4 v[224:225], off
	s_add_i32 m0, s14, 0x2000
	v_lshl_add_u64 v[224:225], s[12:13], 0, v[138:139]
	s_add_u32 s12, s48, 0xc000
	s_addc_u32 s13, s49, 0
	s_add_i32 s14, s64, s17
	global_load_lds_dwordx4 v[224:225], off
	v_lshl_add_u64 v[224:225], s[12:13], 0, v[134:135]
	s_mov_b32 m0, s14
	v_lshl_add_u64 v[144:145], v[144:145], 0, s[36:37]
	global_load_lds_dwordx4 v[224:225], off
	v_lshl_add_u64 v[224:225], s[12:13], 0, v[138:139]
	s_add_i32 m0, s14, 0x2000
	s_nop 0
	global_load_lds_dwordx4 v[224:225], off
	s_mov_b32 m0, s25
	s_nop 0
	global_load_lds_dwordx4 v[144:145], off
	v_lshl_add_u64 v[144:145], v[222:223], 0, s[36:37]
	s_mov_b32 m0, s33
	s_nop 0
	global_load_lds_dwordx4 v[144:145], off
	s_waitcnt vmcnt(8)
	s_waitcnt lgkmcnt(0)
	s_barrier
	v_mfma_f32_16x16x32_bf16 v[76:79], v[158:161], v[190:193], v[76:79]
	v_mfma_f32_16x16x32_bf16 v[76:79], v[162:165], v[194:197], v[76:79]
	v_mfma_f32_16x16x32_bf16 v[52:55], v[166:169], v[190:193], v[52:55]
	v_mfma_f32_16x16x32_bf16 v[52:55], v[170:173], v[194:197], v[52:55]
	v_mfma_f32_16x16x32_bf16 v[36:39], v[166:169], v[198:201], v[36:39]
	v_mfma_f32_16x16x32_bf16 v[36:39], v[170:173], v[202:205], v[36:39]
	v_mfma_f32_16x16x32_bf16 v[48:51], v[158:161], v[198:201], v[48:51]
	v_mfma_f32_16x16x32_bf16 v[48:51], v[162:165], v[202:205], v[48:51]
	v_mfma_f32_16x16x32_bf16 v[32:35], v[158:161], v[206:209], v[32:35]
	v_mfma_f32_16x16x32_bf16 v[32:35], v[162:165], v[210:213], v[32:35]
	v_mfma_f32_16x16x32_bf16 v[20:23], v[166:169], v[206:209], v[20:23]
	v_mfma_f32_16x16x32_bf16 v[20:23], v[170:173], v[210:213], v[20:23]
	v_mfma_f32_16x16x32_bf16 v[4:7], v[166:169], v[214:217], v[4:7]
	v_mfma_f32_16x16x32_bf16 v[4:7], v[170:173], v[218:221], v[4:7]
	v_mfma_f32_16x16x32_bf16 v[16:19], v[158:161], v[214:217], v[16:19]
	v_mfma_f32_16x16x32_bf16 v[16:19], v[162:165], v[218:221], v[16:19]
	v_mfma_f32_16x16x32_bf16 v[12:15], v[174:177], v[214:217], v[12:15]
	v_mfma_f32_16x16x32_bf16 v[12:15], v[178:181], v[218:221], v[12:15]
	v_mfma_f32_16x16x32_bf16 v[8:11], v[182:185], v[214:217], v[8:11]
	v_mfma_f32_16x16x32_bf16 v[8:11], v[186:189], v[218:221], v[8:11]
	v_mfma_f32_16x16x32_bf16 v[24:27], v[182:185], v[206:209], v[24:27]
	v_mfma_f32_16x16x32_bf16 v[24:27], v[186:189], v[210:213], v[24:27]
	v_mfma_f32_16x16x32_bf16 v[28:31], v[174:177], v[206:209], v[28:31]
	v_mfma_f32_16x16x32_bf16 v[28:31], v[178:181], v[210:213], v[28:31]
	v_mfma_f32_16x16x32_bf16 v[44:47], v[174:177], v[198:201], v[44:47]
	v_mfma_f32_16x16x32_bf16 v[44:47], v[178:181], v[202:205], v[44:47]
	v_mfma_f32_16x16x32_bf16 v[40:43], v[182:185], v[198:201], v[40:43]
	v_mfma_f32_16x16x32_bf16 v[40:43], v[186:189], v[202:205], v[40:43]
	v_mfma_f32_16x16x32_bf16 v[56:59], v[182:185], v[190:193], v[56:59]
	v_mfma_f32_16x16x32_bf16 v[56:59], v[186:189], v[194:197], v[56:59]
	v_mfma_f32_16x16x32_bf16 v[60:63], v[174:177], v[190:193], v[60:63]
	v_mfma_f32_16x16x32_bf16 v[60:63], v[178:181], v[194:197], v[60:63]
	s_barrier
	s_add_i32 s0, s0, 2
	s_add_u32 s1, s1, 0x10000
	s_addc_u32 s59, s59, 0
	s_add_u32 s60, s60, 0x100
	s_addc_u32 s61, s61, 0
	s_add_u32 s46, s46, 0xffffff00
	s_addc_u32 s47, s47, -1
	v_lshl_add_u64 v[2:3], v[2:3], 0, s[40:41]
	s_cmpk_gt_u32 s0, 0xa9
	v_lshl_add_u64 v[148:149], v[148:149], 0, s[40:41]
	s_cbranch_scc0 .LBB0_896
	s_and_b64 vcc, exec, s[38:39]
	s_cbranch_vccz .LBB0_899
	s_barrier

.LBB0_1053:
	ds_read_b128 v[146:149], v155
	ds_read_b128 v[160:163], v155 offset:1024
	ds_read_b128 v[164:167], v155 offset:2048
	ds_read_b128 v[168:171], v155 offset:3072
	ds_read_b128 v[172:175], v156
	ds_read_b128 v[176:179], v156 offset:1024
	ds_read_b128 v[180:183], v156 offset:2048
	ds_read_b128 v[184:187], v156 offset:3072
	s_add_u32 s12, s68, s30
	s_addc_u32 s13, s69, 0
	s_cmp_eq_u32 s30, s6
	s_cselect_b32 s23, s0, s13
	s_cselect_b32 s22, s1, s12
	s_cselect_b32 s53, s41, s67
	s_cselect_b32 s52, s64, s66
	s_add_i32 s71, s21, 0xc000
	v_lshl_add_u64 v[220:221], v[2:3], 0, s[30:31]
	s_mov_b32 m0, s71
	s_add_i32 s70, s21, 0xe000
	ds_read_b128 v[188:191], v157
	ds_read_b128 v[192:195], v157 offset:1024
	ds_read_b128 v[196:199], v157 offset:2048
	ds_read_b128 v[200:203], v157 offset:3072
	ds_read_b128 v[204:207], v157 offset:4096
	ds_read_b128 v[208:211], v157 offset:5120
	ds_read_b128 v[212:215], v157 offset:6144
	ds_read_b128 v[216:219], v157 offset:7168
	global_load_lds_dwordx4 v[220:221], off
	v_lshl_add_u64 v[220:221], v[150:151], 0, s[30:31]
	s_mov_b32 m0, s70
	s_nop 0
	global_load_lds_dwordx4 v[220:221], off
	s_waitcnt vmcnt(8)
	s_waitcnt lgkmcnt(0)
	s_barrier
	v_mfma_f32_16x16x32_bf16 v[128:131], v[146:149], v[188:191], v[128:131]
	v_mfma_f32_16x16x32_bf16 v[128:131], v[160:163], v[192:195], v[128:131]
	v_mfma_f32_16x16x32_bf16 v[124:127], v[164:167], v[188:191], v[124:127]
	v_mfma_f32_16x16x32_bf16 v[124:127], v[168:171], v[192:195], v[124:127]
	v_mfma_f32_16x16x32_bf16 v[108:111], v[164:167], v[196:199], v[108:111]
	v_mfma_f32_16x16x32_bf16 v[108:111], v[168:171], v[200:203], v[108:111]
	v_mfma_f32_16x16x32_bf16 v[112:115], v[146:149], v[196:199], v[112:115]
	v_mfma_f32_16x16x32_bf16 v[112:115], v[160:163], v[200:203], v[112:115]
	v_mfma_f32_16x16x32_bf16 v[96:99], v[146:149], v[204:207], v[96:99]
	v_mfma_f32_16x16x32_bf16 v[96:99], v[160:163], v[208:211], v[96:99]
	v_mfma_f32_16x16x32_bf16 v[92:95], v[164:167], v[204:207], v[92:95]
	v_mfma_f32_16x16x32_bf16 v[92:95], v[168:171], v[208:211], v[92:95]
	v_mfma_f32_16x16x32_bf16 v[76:79], v[164:167], v[212:215], v[76:79]
	v_mfma_f32_16x16x32_bf16 v[76:79], v[168:171], v[216:219], v[76:79]
	v_mfma_f32_16x16x32_bf16 v[80:83], v[146:149], v[212:215], v[80:83]
	v_mfma_f32_16x16x32_bf16 v[80:83], v[160:163], v[216:219], v[80:83]
	v_mfma_f32_16x16x32_bf16 v[64:67], v[172:175], v[212:215], v[64:67]
	v_mfma_f32_16x16x32_bf16 v[64:67], v[176:179], v[216:219], v[64:67]
	v_mfma_f32_16x16x32_bf16 v[60:63], v[180:183], v[212:215], v[60:63]
	v_mfma_f32_16x16x32_bf16 v[60:63], v[184:187], v[216:219], v[60:63]
	v_mfma_f32_16x16x32_bf16 v[84:87], v[180:183], v[204:207], v[84:87]
	v_mfma_f32_16x16x32_bf16 v[84:87], v[184:187], v[208:211], v[84:87]
	v_mfma_f32_16x16x32_bf16 v[88:91], v[172:175], v[204:207], v[88:91]
	v_mfma_f32_16x16x32_bf16 v[88:91], v[176:179], v[208:211], v[88:91]
	v_mfma_f32_16x16x32_bf16 v[104:107], v[172:175], v[196:199], v[104:107]
	v_mfma_f32_16x16x32_bf16 v[104:107], v[176:179], v[200:203], v[104:107]
	v_mfma_f32_16x16x32_bf16 v[100:103], v[180:183], v[196:199], v[100:103]
	v_mfma_f32_16x16x32_bf16 v[100:103], v[184:187], v[200:203], v[100:103]
	v_mfma_f32_16x16x32_bf16 v[116:119], v[180:183], v[188:191], v[116:119]
	v_mfma_f32_16x16x32_bf16 v[116:119], v[184:187], v[192:195], v[116:119]
	v_mfma_f32_16x16x32_bf16 v[120:123], v[172:175], v[188:191], v[120:123]
	v_mfma_f32_16x16x32_bf16 v[120:123], v[176:179], v[192:195], v[120:123]
	s_barrier
	s_add_i32 s12, s58, s20
	v_lshl_add_u64 v[220:221], s[52:53], 0, v[134:135]
	s_mov_b32 m0, s12
	ds_read_b128 v[188:191], v157 offset:16384
	ds_read_b128 v[192:195], v157 offset:17408
	ds_read_b128 v[196:199], v157 offset:18432
	ds_read_b128 v[200:203], v157 offset:19456
	ds_read_b128 v[204:207], v157 offset:20480
	ds_read_b128 v[208:211], v157 offset:21504
	ds_read_b128 v[212:215], v157 offset:22528
	ds_read_b128 v[216:219], v157 offset:23552
	global_load_lds_dwordx4 v[220:221], off
	s_add_i32 m0, s12, 0x2000
	s_add_u32 s12, s52, 0x4000
	v_lshl_add_u64 v[220:221], s[52:53], 0, v[138:139]
	s_addc_u32 s13, s53, 0
	s_add_i32 s14, s59, s20
	global_load_lds_dwordx4 v[220:221], off
	v_lshl_add_u64 v[220:221], s[12:13], 0, v[134:135]
	s_mov_b32 m0, s14
	v_lshl_add_u64 v[222:223], s[22:23], 0, v[136:137]
	global_load_lds_dwordx4 v[220:221], off
	v_lshl_add_u64 v[220:221], s[12:13], 0, v[138:139]
	s_add_i32 m0, s14, 0x2000
	s_nop 0
	global_load_lds_dwordx4 v[220:221], off
	v_lshl_add_u64 v[220:221], s[22:23], 0, v[132:133]
	s_mov_b32 m0, s21
	s_nop 0
	global_load_lds_dwordx4 v[220:221], off
	s_mov_b32 m0, s24
	s_nop 0
	global_load_lds_dwordx4 v[222:223], off
	s_waitcnt vmcnt(8)
	s_waitcnt lgkmcnt(0)
	s_barrier
	v_mfma_f32_16x16x32_bf16 v[72:75], v[146:149], v[188:191], v[72:75]
	v_mfma_f32_16x16x32_bf16 v[72:75], v[160:163], v[192:195], v[72:75]
	v_mfma_f32_16x16x32_bf16 v[68:71], v[164:167], v[188:191], v[68:71]
	v_mfma_f32_16x16x32_bf16 v[68:71], v[168:171], v[192:195], v[68:71]
	v_mfma_f32_16x16x32_bf16 v[44:47], v[164:167], v[196:199], v[44:47]
	v_mfma_f32_16x16x32_bf16 v[44:47], v[168:171], v[200:203], v[44:47]
	v_mfma_f32_16x16x32_bf16 v[48:51], v[146:149], v[196:199], v[48:51]
	v_mfma_f32_16x16x32_bf16 v[48:51], v[160:163], v[200:203], v[48:51]
	v_mfma_f32_16x16x32_bf16 v[32:35], v[146:149], v[204:207], v[32:35]
	v_mfma_f32_16x16x32_bf16 v[32:35], v[160:163], v[208:211], v[32:35]
	v_mfma_f32_16x16x32_bf16 v[28:31], v[164:167], v[204:207], v[28:31]
	v_mfma_f32_16x16x32_bf16 v[28:31], v[168:171], v[208:211], v[28:31]
	v_mfma_f32_16x16x32_bf16 v[12:15], v[164:167], v[212:215], v[12:15]
	v_mfma_f32_16x16x32_bf16 v[12:15], v[168:171], v[216:219], v[12:15]
	v_mfma_f32_16x16x32_bf16 v[16:19], v[146:149], v[212:215], v[16:19]
	v_mfma_f32_16x16x32_bf16 v[16:19], v[160:163], v[216:219], v[16:19]
	v_mfma_f32_16x16x32_bf16 v[8:11], v[172:175], v[212:215], v[8:11]
	v_mfma_f32_16x16x32_bf16 v[8:11], v[176:179], v[216:219], v[8:11]
	v_mfma_f32_16x16x32_bf16 v[4:7], v[180:183], v[212:215], v[4:7]
	v_mfma_f32_16x16x32_bf16 v[4:7], v[184:187], v[216:219], v[4:7]
	v_mfma_f32_16x16x32_bf16 v[20:23], v[180:183], v[204:207], v[20:23]
	v_mfma_f32_16x16x32_bf16 v[20:23], v[184:187], v[208:211], v[20:23]
	v_mfma_f32_16x16x32_bf16 v[24:27], v[172:175], v[204:207], v[24:27]
	v_mfma_f32_16x16x32_bf16 v[24:27], v[176:179], v[208:211], v[24:27]
	v_mfma_f32_16x16x32_bf16 v[40:43], v[172:175], v[196:199], v[40:43]
	v_mfma_f32_16x16x32_bf16 v[40:43], v[176:179], v[200:203], v[40:43]
	v_mfma_f32_16x16x32_bf16 v[36:39], v[180:183], v[196:199], v[36:39]
	v_mfma_f32_16x16x32_bf16 v[36:39], v[184:187], v[200:203], v[36:39]
	v_mfma_f32_16x16x32_bf16 v[52:55], v[180:183], v[188:191], v[52:55]
	v_mfma_f32_16x16x32_bf16 v[52:55], v[184:187], v[192:195], v[52:55]
	v_mfma_f32_16x16x32_bf16 v[56:59], v[172:175], v[188:191], v[56:59]
	v_mfma_f32_16x16x32_bf16 v[56:59], v[176:179], v[192:195], v[56:59]
	s_barrier
	s_add_i32 s14, 0, 0x18000
	v_add_u32_e32 v0, s14, v154
	s_add_i32 s72, 0, 0x1c000
	ds_read_b128 v[146:149], v0
	ds_read_b128 v[160:163], v0 offset:1024
	ds_read_b128 v[164:167], v0 offset:2048
	ds_read_b128 v[168:171], v0 offset:3072
	v_add_u32_e32 v0, s72, v154
	ds_read_b128 v[172:175], v0
	ds_read_b128 v[176:179], v0 offset:1024
	ds_read_b128 v[180:183], v0 offset:2048
	ds_read_b128 v[184:187], v0 offset:3072
	s_add_u32 s12, s22, 0x100000
	s_addc_u32 s13, s23, 0
	s_mov_b32 m0, s25
	v_lshl_add_u64 v[224:225], s[12:13], 0, v[132:133]
	ds_read_b128 v[188:191], v157 offset:32768
	ds_read_b128 v[192:195], v157 offset:33792
	ds_read_b128 v[196:199], v157 offset:34816
	ds_read_b128 v[200:203], v157 offset:35840
	ds_read_b128 v[204:207], v157 offset:36864
	ds_read_b128 v[208:211], v157 offset:37888
	ds_read_b128 v[212:215], v157 offset:38912
	ds_read_b128 v[216:219], v157 offset:39936
	global_load_lds_dwordx4 v[224:225], off
	v_lshl_add_u64 v[224:225], s[12:13], 0, v[136:137]
	s_mov_b32 m0, s33
	s_nop 0
	global_load_lds_dwordx4 v[224:225], off
	s_waitcnt vmcnt(8)
	s_waitcnt lgkmcnt(0)
	s_barrier
	v_mfma_f32_16x16x32_bf16 v[128:131], v[146:149], v[188:191], v[128:131]
	v_mfma_f32_16x16x32_bf16 v[128:131], v[160:163], v[192:195], v[128:131]
	v_mfma_f32_16x16x32_bf16 v[124:127], v[164:167], v[188:191], v[124:127]
	v_mfma_f32_16x16x32_bf16 v[124:127], v[168:171], v[192:195], v[124:127]
	v_mfma_f32_16x16x32_bf16 v[108:111], v[164:167], v[196:199], v[108:111]
	v_mfma_f32_16x16x32_bf16 v[108:111], v[168:171], v[200:203], v[108:111]
	v_mfma_f32_16x16x32_bf16 v[112:115], v[146:149], v[196:199], v[112:115]
	v_mfma_f32_16x16x32_bf16 v[112:115], v[160:163], v[200:203], v[112:115]
	v_mfma_f32_16x16x32_bf16 v[96:99], v[146:149], v[204:207], v[96:99]
	v_mfma_f32_16x16x32_bf16 v[96:99], v[160:163], v[208:211], v[96:99]
	v_mfma_f32_16x16x32_bf16 v[92:95], v[164:167], v[204:207], v[92:95]
	v_mfma_f32_16x16x32_bf16 v[92:95], v[168:171], v[208:211], v[92:95]
	v_mfma_f32_16x16x32_bf16 v[76:79], v[164:167], v[212:215], v[76:79]
	v_mfma_f32_16x16x32_bf16 v[76:79], v[168:171], v[216:219], v[76:79]
	v_mfma_f32_16x16x32_bf16 v[80:83], v[146:149], v[212:215], v[80:83]
	v_mfma_f32_16x16x32_bf16 v[80:83], v[160:163], v[216:219], v[80:83]
	v_mfma_f32_16x16x32_bf16 v[64:67], v[172:175], v[212:215], v[64:67]
	v_mfma_f32_16x16x32_bf16 v[64:67], v[176:179], v[216:219], v[64:67]
	v_mfma_f32_16x16x32_bf16 v[60:63], v[180:183], v[212:215], v[60:63]
	v_mfma_f32_16x16x32_bf16 v[60:63], v[184:187], v[216:219], v[60:63]
	v_mfma_f32_16x16x32_bf16 v[84:87], v[180:183], v[204:207], v[84:87]
	v_mfma_f32_16x16x32_bf16 v[84:87], v[184:187], v[208:211], v[84:87]
	v_mfma_f32_16x16x32_bf16 v[88:91], v[172:175], v[204:207], v[88:91]
	v_mfma_f32_16x16x32_bf16 v[88:91], v[176:179], v[208:211], v[88:91]
	v_mfma_f32_16x16x32_bf16 v[104:107], v[172:175], v[196:199], v[104:107]
	v_mfma_f32_16x16x32_bf16 v[104:107], v[176:179], v[200:203], v[104:107]
	v_mfma_f32_16x16x32_bf16 v[100:103], v[180:183], v[196:199], v[100:103]
	v_mfma_f32_16x16x32_bf16 v[100:103], v[184:187], v[200:203], v[100:103]
	v_mfma_f32_16x16x32_bf16 v[116:119], v[180:183], v[188:191], v[116:119]
	v_mfma_f32_16x16x32_bf16 v[116:119], v[184:187], v[192:195], v[116:119]
	v_mfma_f32_16x16x32_bf16 v[120:123], v[172:175], v[188:191], v[120:123]
	v_mfma_f32_16x16x32_bf16 v[120:123], v[176:179], v[192:195], v[120:123]
	s_barrier
	s_add_u32 s12, s52, 0x8000
	s_addc_u32 s13, s53, 0
	s_add_i32 s14, s14, s20
	v_lshl_add_u64 v[224:225], s[12:13], 0, v[134:135]
	s_mov_b32 m0, s14
	ds_read_b128 v[188:191], v157 offset:49152
	ds_read_b128 v[192:195], v157 offset:50176
	ds_read_b128 v[196:199], v157 offset:51200
	ds_read_b128 v[200:203], v157 offset:52224
	ds_read_b128 v[204:207], v157 offset:53248
	ds_read_b128 v[208:211], v157 offset:54272
	ds_read_b128 v[212:215], v157 offset:55296
	ds_read_b128 v[216:219], v157 offset:56320
	global_load_lds_dwordx4 v[224:225], off
	s_add_i32 m0, s14, 0x2000
	v_lshl_add_u64 v[224:225], s[12:13], 0, v[138:139]
	s_add_u32 s12, s52, 0xc000
	s_addc_u32 s13, s53, 0
	s_add_i32 s14, s72, s20
	global_load_lds_dwordx4 v[224:225], off
	v_lshl_add_u64 v[224:225], s[12:13], 0, v[134:135]
	s_mov_b32 m0, s14
	v_lshl_add_u64 v[220:221], v[220:221], 0, s[28:29]
	global_load_lds_dwordx4 v[224:225], off
	v_lshl_add_u64 v[224:225], s[12:13], 0, v[138:139]
	s_add_i32 m0, s14, 0x2000
	s_nop 0
	global_load_lds_dwordx4 v[224:225], off
	s_mov_b32 m0, s54
	s_nop 0
	global_load_lds_dwordx4 v[220:221], off
	v_lshl_add_u64 v[220:221], v[222:223], 0, s[28:29]
	s_mov_b32 m0, s55
	s_nop 0
	global_load_lds_dwordx4 v[220:221], off
	s_waitcnt vmcnt(8)
	s_waitcnt lgkmcnt(0)
	s_barrier
	v_mfma_f32_16x16x32_bf16 v[72:75], v[146:149], v[188:191], v[72:75]
	v_mfma_f32_16x16x32_bf16 v[72:75], v[160:163], v[192:195], v[72:75]
	v_mfma_f32_16x16x32_bf16 v[68:71], v[164:167], v[188:191], v[68:71]
	v_mfma_f32_16x16x32_bf16 v[68:71], v[168:171], v[192:195], v[68:71]
	v_mfma_f32_16x16x32_bf16 v[44:47], v[164:167], v[196:199], v[44:47]
	v_mfma_f32_16x16x32_bf16 v[44:47], v[168:171], v[200:203], v[44:47]
	v_mfma_f32_16x16x32_bf16 v[48:51], v[146:149], v[196:199], v[48:51]
	v_mfma_f32_16x16x32_bf16 v[48:51], v[160:163], v[200:203], v[48:51]
	v_mfma_f32_16x16x32_bf16 v[32:35], v[146:149], v[204:207], v[32:35]
	v_mfma_f32_16x16x32_bf16 v[32:35], v[160:163], v[208:211], v[32:35]
	v_mfma_f32_16x16x32_bf16 v[28:31], v[164:167], v[204:207], v[28:31]
	v_mfma_f32_16x16x32_bf16 v[28:31], v[168:171], v[208:211], v[28:31]
	v_mfma_f32_16x16x32_bf16 v[12:15], v[164:167], v[212:215], v[12:15]
	v_mfma_f32_16x16x32_bf16 v[12:15], v[168:171], v[216:219], v[12:15]
	v_mfma_f32_16x16x32_bf16 v[16:19], v[146:149], v[212:215], v[16:19]
	v_mfma_f32_16x16x32_bf16 v[16:19], v[160:163], v[216:219], v[16:19]
	v_mfma_f32_16x16x32_bf16 v[8:11], v[172:175], v[212:215], v[8:11]
	v_mfma_f32_16x16x32_bf16 v[8:11], v[176:179], v[216:219], v[8:11]
	v_mfma_f32_16x16x32_bf16 v[4:7], v[180:183], v[212:215], v[4:7]
	v_mfma_f32_16x16x32_bf16 v[4:7], v[184:187], v[216:219], v[4:7]
	v_mfma_f32_16x16x32_bf16 v[20:23], v[180:183], v[204:207], v[20:23]
	v_mfma_f32_16x16x32_bf16 v[20:23], v[184:187], v[208:211], v[20:23]
	v_mfma_f32_16x16x32_bf16 v[24:27], v[172:175], v[204:207], v[24:27]
	v_mfma_f32_16x16x32_bf16 v[24:27], v[176:179], v[208:211], v[24:27]
	v_mfma_f32_16x16x32_bf16 v[40:43], v[172:175], v[196:199], v[40:43]
	v_mfma_f32_16x16x32_bf16 v[40:43], v[176:179], v[200:203], v[40:43]
	v_mfma_f32_16x16x32_bf16 v[36:39], v[180:183], v[196:199], v[36:39]
	v_mfma_f32_16x16x32_bf16 v[36:39], v[184:187], v[200:203], v[36:39]
	v_mfma_f32_16x16x32_bf16 v[52:55], v[180:183], v[188:191], v[52:55]
	v_mfma_f32_16x16x32_bf16 v[52:55], v[184:187], v[192:195], v[52:55]
	v_mfma_f32_16x16x32_bf16 v[56:59], v[172:175], v[188:191], v[56:59]
	v_mfma_f32_16x16x32_bf16 v[56:59], v[176:179], v[192:195], v[56:59]
	s_barrier
	s_add_i32 s65, s65, 2
	s_add_u32 s66, s66, 0x10000
	s_addc_u32 s67, s67, 0
	s_add_u32 s68, s68, 0x100
	s_addc_u32 s69, s69, 0
	s_add_u32 s6, s6, 0xffffff00
	s_addc_u32 s7, s7, -1
	v_lshl_add_u64 v[2:3], v[2:3], 0, s[36:37]
	s_cmp_gt_u32 s65, 61
	v_lshl_add_u64 v[150:151], v[150:151], 0, s[36:37]
	s_cbranch_scc0 .LBB0_1053
	s_and_b64 vcc, exec, s[34:35]
	s_cbranch_vccnz .LBB0_1061
	s_and_b64 s[0:1], s[10:11], s[4:5]
	s_andn2_b64 vcc, exec, s[0:1]
	s_cbranch_vccz .LBB0_1062

.LBB0_1734:
	ds_read_b128 v[158:161], v153
	ds_read_b128 v[162:165], v153 offset:1024
	ds_read_b128 v[166:169], v153 offset:2048
	ds_read_b128 v[170:173], v153 offset:3072
	ds_read_b128 v[174:177], v154
	ds_read_b128 v[178:181], v154 offset:1024
	ds_read_b128 v[182:185], v154 offset:2048
	ds_read_b128 v[186:189], v154 offset:3072
	s_add_u32 s12, s60, s24
	s_addc_u32 s13, s61, 0
	s_cmp_eq_u32 s24, s44
	s_cselect_b32 s23, s9, s13
	s_cselect_b32 s22, s8, s12
	s_cselect_b32 s47, s43, s59
	s_cselect_b32 s46, s42, s1
	s_add_i32 s63, s18, 0xc000
	v_lshl_add_u64 v[144:145], v[2:3], 0, s[24:25]
	s_mov_b32 m0, s63
	s_add_i32 s62, s18, 0xe000
	ds_read_b128 v[190:193], v155
	ds_read_b128 v[194:197], v155 offset:1024
	ds_read_b128 v[198:201], v155 offset:2048
	ds_read_b128 v[202:205], v155 offset:3072
	ds_read_b128 v[206:209], v155 offset:4096
	ds_read_b128 v[210:213], v155 offset:5120
	ds_read_b128 v[214:217], v155 offset:6144
	ds_read_b128 v[218:221], v155 offset:7168
	global_load_lds_dwordx4 v[144:145], off
	v_lshl_add_u64 v[144:145], v[148:149], 0, s[24:25]
	s_mov_b32 m0, s62
	s_nop 0
	global_load_lds_dwordx4 v[144:145], off
	s_waitcnt vmcnt(8)
	s_waitcnt lgkmcnt(0)
	s_barrier
	v_mfma_f32_16x16x32_bf16 v[128:131], v[158:161], v[190:193], v[128:131]
	v_mfma_f32_16x16x32_bf16 v[128:131], v[162:165], v[194:197], v[128:131]
	v_mfma_f32_16x16x32_bf16 v[116:119], v[166:169], v[190:193], v[116:119]
	v_mfma_f32_16x16x32_bf16 v[116:119], v[170:173], v[194:197], v[116:119]
	v_mfma_f32_16x16x32_bf16 v[100:103], v[166:169], v[198:201], v[100:103]
	v_mfma_f32_16x16x32_bf16 v[100:103], v[170:173], v[202:205], v[100:103]
	v_mfma_f32_16x16x32_bf16 v[112:115], v[158:161], v[198:201], v[112:115]
	v_mfma_f32_16x16x32_bf16 v[112:115], v[162:165], v[202:205], v[112:115]
	v_mfma_f32_16x16x32_bf16 v[96:99], v[158:161], v[206:209], v[96:99]
	v_mfma_f32_16x16x32_bf16 v[96:99], v[162:165], v[210:213], v[96:99]
	v_mfma_f32_16x16x32_bf16 v[84:87], v[166:169], v[206:209], v[84:87]
	v_mfma_f32_16x16x32_bf16 v[84:87], v[170:173], v[210:213], v[84:87]
	v_mfma_f32_16x16x32_bf16 v[64:67], v[166:169], v[214:217], v[64:67]
	v_mfma_f32_16x16x32_bf16 v[64:67], v[170:173], v[218:221], v[64:67]
	v_mfma_f32_16x16x32_bf16 v[80:83], v[158:161], v[214:217], v[80:83]
	v_mfma_f32_16x16x32_bf16 v[80:83], v[162:165], v[218:221], v[80:83]
	v_mfma_f32_16x16x32_bf16 v[72:75], v[174:177], v[214:217], v[72:75]
	v_mfma_f32_16x16x32_bf16 v[72:75], v[178:181], v[218:221], v[72:75]
	v_mfma_f32_16x16x32_bf16 v[68:71], v[182:185], v[214:217], v[68:71]
	v_mfma_f32_16x16x32_bf16 v[68:71], v[186:189], v[218:221], v[68:71]
	v_mfma_f32_16x16x32_bf16 v[88:91], v[182:185], v[206:209], v[88:91]
	v_mfma_f32_16x16x32_bf16 v[88:91], v[186:189], v[210:213], v[88:91]
	v_mfma_f32_16x16x32_bf16 v[92:95], v[174:177], v[206:209], v[92:95]
	v_mfma_f32_16x16x32_bf16 v[92:95], v[178:181], v[210:213], v[92:95]
	v_mfma_f32_16x16x32_bf16 v[108:111], v[174:177], v[198:201], v[108:111]
	v_mfma_f32_16x16x32_bf16 v[108:111], v[178:181], v[202:205], v[108:111]
	v_mfma_f32_16x16x32_bf16 v[104:107], v[182:185], v[198:201], v[104:107]
	v_mfma_f32_16x16x32_bf16 v[104:107], v[186:189], v[202:205], v[104:107]
	v_mfma_f32_16x16x32_bf16 v[120:123], v[182:185], v[190:193], v[120:123]
	v_mfma_f32_16x16x32_bf16 v[120:123], v[186:189], v[194:197], v[120:123]
	v_mfma_f32_16x16x32_bf16 v[124:127], v[174:177], v[190:193], v[124:127]
	v_mfma_f32_16x16x32_bf16 v[124:127], v[178:181], v[194:197], v[124:127]
	s_barrier
	s_add_i32 s12, s52, s17
	v_lshl_add_u64 v[144:145], s[46:47], 0, v[134:135]
	s_mov_b32 m0, s12
	ds_read_b128 v[190:193], v155 offset:16384
	ds_read_b128 v[194:197], v155 offset:17408
	ds_read_b128 v[198:201], v155 offset:18432
	ds_read_b128 v[202:205], v155 offset:19456
	ds_read_b128 v[206:209], v155 offset:20480
	ds_read_b128 v[210:213], v155 offset:21504
	ds_read_b128 v[214:217], v155 offset:22528
	ds_read_b128 v[218:221], v155 offset:23552
	global_load_lds_dwordx4 v[144:145], off
	s_add_i32 m0, s12, 0x2000
	s_add_u32 s12, s46, 0x4000
	v_lshl_add_u64 v[144:145], s[46:47], 0, v[138:139]
	s_addc_u32 s13, s47, 0
	s_add_i32 s14, s53, s17
	global_load_lds_dwordx4 v[144:145], off
	v_lshl_add_u64 v[144:145], s[12:13], 0, v[134:135]
	s_mov_b32 m0, s14
	v_lshl_add_u64 v[222:223], s[22:23], 0, v[136:137]
	global_load_lds_dwordx4 v[144:145], off
	v_lshl_add_u64 v[144:145], s[12:13], 0, v[138:139]
	s_add_i32 m0, s14, 0x2000
	s_nop 0
	global_load_lds_dwordx4 v[144:145], off
	v_lshl_add_u64 v[144:145], s[22:23], 0, v[132:133]
	s_mov_b32 m0, s18
	s_nop 0
	global_load_lds_dwordx4 v[144:145], off
	s_mov_b32 m0, s19
	s_nop 0
	global_load_lds_dwordx4 v[222:223], off
	s_waitcnt vmcnt(8)
	s_waitcnt lgkmcnt(0)
	s_barrier
	v_mfma_f32_16x16x32_bf16 v[76:79], v[158:161], v[190:193], v[76:79]
	v_mfma_f32_16x16x32_bf16 v[76:79], v[162:165], v[194:197], v[76:79]
	v_mfma_f32_16x16x32_bf16 v[52:55], v[166:169], v[190:193], v[52:55]
	v_mfma_f32_16x16x32_bf16 v[52:55], v[170:173], v[194:197], v[52:55]
	v_mfma_f32_16x16x32_bf16 v[36:39], v[166:169], v[198:201], v[36:39]
	v_mfma_f32_16x16x32_bf16 v[36:39], v[170:173], v[202:205], v[36:39]
	v_mfma_f32_16x16x32_bf16 v[48:51], v[158:161], v[198:201], v[48:51]
	v_mfma_f32_16x16x32_bf16 v[48:51], v[162:165], v[202:205], v[48:51]
	v_mfma_f32_16x16x32_bf16 v[32:35], v[158:161], v[206:209], v[32:35]
	v_mfma_f32_16x16x32_bf16 v[32:35], v[162:165], v[210:213], v[32:35]
	v_mfma_f32_16x16x32_bf16 v[20:23], v[166:169], v[206:209], v[20:23]
	v_mfma_f32_16x16x32_bf16 v[20:23], v[170:173], v[210:213], v[20:23]
	v_mfma_f32_16x16x32_bf16 v[4:7], v[166:169], v[214:217], v[4:7]
	v_mfma_f32_16x16x32_bf16 v[4:7], v[170:173], v[218:221], v[4:7]
	v_mfma_f32_16x16x32_bf16 v[16:19], v[158:161], v[214:217], v[16:19]
	v_mfma_f32_16x16x32_bf16 v[16:19], v[162:165], v[218:221], v[16:19]
	v_mfma_f32_16x16x32_bf16 v[12:15], v[174:177], v[214:217], v[12:15]
	v_mfma_f32_16x16x32_bf16 v[12:15], v[178:181], v[218:221], v[12:15]
	v_mfma_f32_16x16x32_bf16 v[8:11], v[182:185], v[214:217], v[8:11]
	v_mfma_f32_16x16x32_bf16 v[8:11], v[186:189], v[218:221], v[8:11]
	v_mfma_f32_16x16x32_bf16 v[24:27], v[182:185], v[206:209], v[24:27]
	v_mfma_f32_16x16x32_bf16 v[24:27], v[186:189], v[210:213], v[24:27]
	v_mfma_f32_16x16x32_bf16 v[28:31], v[174:177], v[206:209], v[28:31]
	v_mfma_f32_16x16x32_bf16 v[28:31], v[178:181], v[210:213], v[28:31]
	v_mfma_f32_16x16x32_bf16 v[44:47], v[174:177], v[198:201], v[44:47]
	v_mfma_f32_16x16x32_bf16 v[44:47], v[178:181], v[202:205], v[44:47]
	v_mfma_f32_16x16x32_bf16 v[40:43], v[182:185], v[198:201], v[40:43]
	v_mfma_f32_16x16x32_bf16 v[40:43], v[186:189], v[202:205], v[40:43]
	v_mfma_f32_16x16x32_bf16 v[56:59], v[182:185], v[190:193], v[56:59]
	v_mfma_f32_16x16x32_bf16 v[56:59], v[186:189], v[194:197], v[56:59]
	v_mfma_f32_16x16x32_bf16 v[60:63], v[174:177], v[190:193], v[60:63]
	v_mfma_f32_16x16x32_bf16 v[60:63], v[178:181], v[194:197], v[60:63]
	s_barrier
	s_add_i32 s14, 0, 0x18000
	v_add_u32_e32 v1, s14, v151
	s_add_i32 s64, 0, 0x1c000
	ds_read_b128 v[158:161], v1
	ds_read_b128 v[162:165], v1 offset:1024
	ds_read_b128 v[166:169], v1 offset:2048
	ds_read_b128 v[170:173], v1 offset:3072
	v_add_u32_e32 v1, s64, v151
	ds_read_b128 v[174:177], v1
	ds_read_b128 v[178:181], v1 offset:1024
	ds_read_b128 v[182:185], v1 offset:2048
	ds_read_b128 v[186:189], v1 offset:3072
	s_add_u32 s12, s22, 0x2b0000
	s_addc_u32 s13, s23, 0
	s_mov_b32 m0, s20
	v_lshl_add_u64 v[224:225], s[12:13], 0, v[132:133]
	ds_read_b128 v[190:193], v155 offset:32768
	ds_read_b128 v[194:197], v155 offset:33792
	ds_read_b128 v[198:201], v155 offset:34816
	ds_read_b128 v[202:205], v155 offset:35840
	ds_read_b128 v[206:209], v155 offset:36864
	ds_read_b128 v[210:213], v155 offset:37888
	ds_read_b128 v[214:217], v155 offset:38912
	ds_read_b128 v[218:221], v155 offset:39936
	global_load_lds_dwordx4 v[224:225], off
	v_lshl_add_u64 v[224:225], s[12:13], 0, v[136:137]
	s_mov_b32 m0, s21
	s_nop 0
	global_load_lds_dwordx4 v[224:225], off
	s_waitcnt vmcnt(8)
	s_waitcnt lgkmcnt(0)
	s_barrier
	v_mfma_f32_16x16x32_bf16 v[128:131], v[158:161], v[190:193], v[128:131]
	v_mfma_f32_16x16x32_bf16 v[128:131], v[162:165], v[194:197], v[128:131]
	v_mfma_f32_16x16x32_bf16 v[116:119], v[166:169], v[190:193], v[116:119]
	v_mfma_f32_16x16x32_bf16 v[116:119], v[170:173], v[194:197], v[116:119]
	v_mfma_f32_16x16x32_bf16 v[100:103], v[166:169], v[198:201], v[100:103]
	v_mfma_f32_16x16x32_bf16 v[100:103], v[170:173], v[202:205], v[100:103]
	v_mfma_f32_16x16x32_bf16 v[112:115], v[158:161], v[198:201], v[112:115]
	v_mfma_f32_16x16x32_bf16 v[112:115], v[162:165], v[202:205], v[112:115]
	v_mfma_f32_16x16x32_bf16 v[96:99], v[158:161], v[206:209], v[96:99]
	v_mfma_f32_16x16x32_bf16 v[96:99], v[162:165], v[210:213], v[96:99]
	v_mfma_f32_16x16x32_bf16 v[84:87], v[166:169], v[206:209], v[84:87]
	v_mfma_f32_16x16x32_bf16 v[84:87], v[170:173], v[210:213], v[84:87]
	v_mfma_f32_16x16x32_bf16 v[64:67], v[166:169], v[214:217], v[64:67]
	v_mfma_f32_16x16x32_bf16 v[64:67], v[170:173], v[218:221], v[64:67]
	v_mfma_f32_16x16x32_bf16 v[80:83], v[158:161], v[214:217], v[80:83]
	v_mfma_f32_16x16x32_bf16 v[80:83], v[162:165], v[218:221], v[80:83]
	v_mfma_f32_16x16x32_bf16 v[72:75], v[174:177], v[214:217], v[72:75]
	v_mfma_f32_16x16x32_bf16 v[72:75], v[178:181], v[218:221], v[72:75]
	v_mfma_f32_16x16x32_bf16 v[68:71], v[182:185], v[214:217], v[68:71]
	v_mfma_f32_16x16x32_bf16 v[68:71], v[186:189], v[218:221], v[68:71]
	v_mfma_f32_16x16x32_bf16 v[88:91], v[182:185], v[206:209], v[88:91]
	v_mfma_f32_16x16x32_bf16 v[88:91], v[186:189], v[210:213], v[88:91]
	v_mfma_f32_16x16x32_bf16 v[92:95], v[174:177], v[206:209], v[92:95]
	v_mfma_f32_16x16x32_bf16 v[92:95], v[178:181], v[210:213], v[92:95]
	v_mfma_f32_16x16x32_bf16 v[108:111], v[174:177], v[198:201], v[108:111]
	v_mfma_f32_16x16x32_bf16 v[108:111], v[178:181], v[202:205], v[108:111]
	v_mfma_f32_16x16x32_bf16 v[104:107], v[182:185], v[198:201], v[104:107]
	v_mfma_f32_16x16x32_bf16 v[104:107], v[186:189], v[202:205], v[104:107]
	v_mfma_f32_16x16x32_bf16 v[120:123], v[182:185], v[190:193], v[120:123]
	v_mfma_f32_16x16x32_bf16 v[120:123], v[186:189], v[194:197], v[120:123]
	v_mfma_f32_16x16x32_bf16 v[124:127], v[174:177], v[190:193], v[124:127]
	v_mfma_f32_16x16x32_bf16 v[124:127], v[178:181], v[194:197], v[124:127]
	s_barrier
	s_add_u32 s12, s46, 0x8000
	s_addc_u32 s13, s47, 0
	s_add_i32 s14, s14, s17
	v_lshl_add_u64 v[224:225], s[12:13], 0, v[134:135]
	s_mov_b32 m0, s14
	ds_read_b128 v[190:193], v155 offset:49152
	ds_read_b128 v[194:197], v155 offset:50176
	ds_read_b128 v[198:201], v155 offset:51200
	ds_read_b128 v[202:205], v155 offset:52224
	ds_read_b128 v[206:209], v155 offset:53248
	ds_read_b128 v[210:213], v155 offset:54272
	ds_read_b128 v[214:217], v155 offset:55296
	ds_read_b128 v[218:221], v155 offset:56320
	global_load_lds_dwordx4 v[224:225], off
	s_add_i32 m0, s14, 0x2000
	v_lshl_add_u64 v[224:225], s[12:13], 0, v[138:139]
	s_add_u32 s12, s46, 0xc000
	s_addc_u32 s13, s47, 0
	s_add_i32 s14, s64, s17
	global_load_lds_dwordx4 v[224:225], off
	v_lshl_add_u64 v[224:225], s[12:13], 0, v[134:135]
	s_mov_b32 m0, s14
	v_lshl_add_u64 v[144:145], v[144:145], 0, s[34:35]
	global_load_lds_dwordx4 v[224:225], off
	v_lshl_add_u64 v[224:225], s[12:13], 0, v[138:139]
	s_add_i32 m0, s14, 0x2000
	s_nop 0
	global_load_lds_dwordx4 v[224:225], off
	s_mov_b32 m0, s48
	s_nop 0
	global_load_lds_dwordx4 v[144:145], off
	v_lshl_add_u64 v[144:145], v[222:223], 0, s[34:35]
	s_mov_b32 m0, s49
	s_nop 0
	global_load_lds_dwordx4 v[144:145], off
	s_waitcnt vmcnt(8)
	s_waitcnt lgkmcnt(0)
	s_barrier
	v_mfma_f32_16x16x32_bf16 v[76:79], v[158:161], v[190:193], v[76:79]
	v_mfma_f32_16x16x32_bf16 v[76:79], v[162:165], v[194:197], v[76:79]
	v_mfma_f32_16x16x32_bf16 v[52:55], v[166:169], v[190:193], v[52:55]
	v_mfma_f32_16x16x32_bf16 v[52:55], v[170:173], v[194:197], v[52:55]
	v_mfma_f32_16x16x32_bf16 v[36:39], v[166:169], v[198:201], v[36:39]
	v_mfma_f32_16x16x32_bf16 v[36:39], v[170:173], v[202:205], v[36:39]
	v_mfma_f32_16x16x32_bf16 v[48:51], v[158:161], v[198:201], v[48:51]
	v_mfma_f32_16x16x32_bf16 v[48:51], v[162:165], v[202:205], v[48:51]
	v_mfma_f32_16x16x32_bf16 v[32:35], v[158:161], v[206:209], v[32:35]
	v_mfma_f32_16x16x32_bf16 v[32:35], v[162:165], v[210:213], v[32:35]
	v_mfma_f32_16x16x32_bf16 v[20:23], v[166:169], v[206:209], v[20:23]
	v_mfma_f32_16x16x32_bf16 v[20:23], v[170:173], v[210:213], v[20:23]
	v_mfma_f32_16x16x32_bf16 v[4:7], v[166:169], v[214:217], v[4:7]
	v_mfma_f32_16x16x32_bf16 v[4:7], v[170:173], v[218:221], v[4:7]
	v_mfma_f32_16x16x32_bf16 v[16:19], v[158:161], v[214:217], v[16:19]
	v_mfma_f32_16x16x32_bf16 v[16:19], v[162:165], v[218:221], v[16:19]
	v_mfma_f32_16x16x32_bf16 v[12:15], v[174:177], v[214:217], v[12:15]
	v_mfma_f32_16x16x32_bf16 v[12:15], v[178:181], v[218:221], v[12:15]
	v_mfma_f32_16x16x32_bf16 v[8:11], v[182:185], v[214:217], v[8:11]
	v_mfma_f32_16x16x32_bf16 v[8:11], v[186:189], v[218:221], v[8:11]
	v_mfma_f32_16x16x32_bf16 v[24:27], v[182:185], v[206:209], v[24:27]
	v_mfma_f32_16x16x32_bf16 v[24:27], v[186:189], v[210:213], v[24:27]
	v_mfma_f32_16x16x32_bf16 v[28:31], v[174:177], v[206:209], v[28:31]
	v_mfma_f32_16x16x32_bf16 v[28:31], v[178:181], v[210:213], v[28:31]
	v_mfma_f32_16x16x32_bf16 v[44:47], v[174:177], v[198:201], v[44:47]
	v_mfma_f32_16x16x32_bf16 v[44:47], v[178:181], v[202:205], v[44:47]
	v_mfma_f32_16x16x32_bf16 v[40:43], v[182:185], v[198:201], v[40:43]
	v_mfma_f32_16x16x32_bf16 v[40:43], v[186:189], v[202:205], v[40:43]
	v_mfma_f32_16x16x32_bf16 v[56:59], v[182:185], v[190:193], v[56:59]
	v_mfma_f32_16x16x32_bf16 v[56:59], v[186:189], v[194:197], v[56:59]
	v_mfma_f32_16x16x32_bf16 v[60:63], v[174:177], v[190:193], v[60:63]
	v_mfma_f32_16x16x32_bf16 v[60:63], v[178:181], v[194:197], v[60:63]
	s_barrier
	s_add_i32 s0, s0, 2
	s_add_u32 s1, s1, 0x10000
	s_addc_u32 s59, s59, 0
	s_add_u32 s60, s60, 0x100
	s_addc_u32 s61, s61, 0
	s_add_u32 s44, s44, 0xffffff00
	s_addc_u32 s45, s45, -1
	v_lshl_add_u64 v[2:3], v[2:3], 0, s[38:39]
	s_cmpk_gt_u32 s0, 0xa9
	v_lshl_add_u64 v[148:149], v[148:149], 0, s[38:39]
	s_cbranch_scc0 .LBB0_1734
	s_and_b64 vcc, exec, s[36:37]
	s_cbranch_vccz .LBB0_1737
	s_barrier
